# v51 + pool phase: next batch's rows requested at the start of the batch too (gains staged in LDS free the registers the reduction needs)
# speedup vs baseline: 1.0022x; 1.0007x over previous
.Lp1f_entry:
	s_waitcnt lgkmcnt(0)
	s_barrier
	v_readlane_b32 s8, v251, 48
	v_readlane_b32 s9, v251, 54
	v_readlane_b32 s2, v251, 16
	v_readlane_b32 s3, v251, 17
	v_readlane_b32 s6, v251, 20
	v_readlane_b32 s7, v251, 21
	v_readlane_b32 s4, v251, 2
	v_readlane_b32 s5, v251, 3
	s_nop 1
	s_lshr_b32 s9, s9, 6
	s_lshl_b32 s10, s8, 6
	s_and_b32 s11, s10, 0x1fff
	s_lshr_b32 s52, s9, 1
	s_lshl_b32 s12, 2, s52
	s_lshl_b32 s52, s9, 11
	s_add_u32 s2, s2, s52
	s_addc_u32 s3, s3, 0
	s_add_u32 s6, s6, s52
	s_addc_u32 s7, s7, 0
	s_add_u32 s4, s4, 0x29000000
	s_addc_u32 s5, s5, 0
	s_lshl_b32 s52, s9, 10
	s_add_u32 s4, s4, s52
	s_addc_u32 s5, s5, 0
	v_mbcnt_lo_u32_b32 v1, -1, 0
	v_mbcnt_hi_u32_b32 v1, -1, v1
	v_lshlrev_b32_e32 v3, 3, v1
	v_lshlrev_b32_e32 v1, 4, v1
	global_load_dwordx4 v[4:7], v1, s[6:7]
	global_load_dwordx4 v[8:11], v1, s[6:7] offset:1024
	v_mov_b32_e32 v208, 0
	v_mov_b32_e32 v209, 0
	v_mov_b32_e32 v210, 0
	v_mov_b32_e32 v211, 0
	v_mov_b32_e32 v212, 0
	v_mov_b32_e32 v213, 0
	v_mov_b32_e32 v214, 0
	v_mov_b32_e32 v215, 0
	s_lshl_b32 s28, s9, 11
	s_add_i32 s28, s28, 0x1400
	v_lshlrev_b32_e32 v217, 1, v1
	v_add_u32_e32 v217, s28, v217
	s_waitcnt vmcnt(0)
	ds_write_b128 v217, v[4:7]
	ds_write_b128 v217, v[8:11] offset:16
	s_cmp_eq_u32 s11, 0
	s_cbranch_scc1 .Lp1f_nohalo
	s_mov_b32 s13, 0
	s_sub_i32 s14, s10, 16
	s_sub_i32 s15, s11, 16
	s_add_i32 s52, s14, 0
	s_mov_b32 s53, 0
	s_lshl_b64 s[52:53], s[52:53], 14
	s_add_u32 s52, s52, s2
	s_addc_u32 s53, s53, s3
	global_load_dwordx4 v[16:19], v1, s[52:53]
	global_load_dwordx4 v[20:23], v1, s[52:53] offset:1024
	s_add_i32 s52, s14, 1
	s_mov_b32 s53, 0
	s_lshl_b64 s[52:53], s[52:53], 14
	s_add_u32 s52, s52, s2
	s_addc_u32 s53, s53, s3
	global_load_dwordx4 v[24:27], v1, s[52:53]
	global_load_dwordx4 v[28:31], v1, s[52:53] offset:1024
	s_add_i32 s52, s14, 2
	s_mov_b32 s53, 0
	s_lshl_b64 s[52:53], s[52:53], 14
	s_add_u32 s52, s52, s2
	s_addc_u32 s53, s53, s3
	global_load_dwordx4 v[32:35], v1, s[52:53]
	global_load_dwordx4 v[36:39], v1, s[52:53] offset:1024
	s_add_i32 s52, s14, 3
	s_mov_b32 s53, 0
	s_lshl_b64 s[52:53], s[52:53], 14
	s_add_u32 s52, s52, s2
	s_addc_u32 s53, s53, s3
	global_load_dwordx4 v[40:43], v1, s[52:53]
	global_load_dwordx4 v[44:47], v1, s[52:53] offset:1024
	s_add_i32 s52, s14, 4
	s_mov_b32 s53, 0
	s_lshl_b64 s[52:53], s[52:53], 14
	s_add_u32 s52, s52, s2
	s_addc_u32 s53, s53, s3
	global_load_dwordx4 v[48:51], v1, s[52:53]
	global_load_dwordx4 v[52:55], v1, s[52:53] offset:1024
	s_add_i32 s52, s14, 5
	s_mov_b32 s53, 0
	s_lshl_b64 s[52:53], s[52:53], 14
	s_add_u32 s52, s52, s2
	s_addc_u32 s53, s53, s3
	global_load_dwordx4 v[56:59], v1, s[52:53]
	global_load_dwordx4 v[60:63], v1, s[52:53] offset:1024
	s_add_i32 s52, s14, 6
	s_mov_b32 s53, 0
	s_lshl_b64 s[52:53], s[52:53], 14
	s_add_u32 s52, s52, s2
	s_addc_u32 s53, s53, s3
	global_load_dwordx4 v[64:67], v1, s[52:53]
	global_load_dwordx4 v[68:71], v1, s[52:53] offset:1024
	s_add_i32 s52, s14, 7
	s_mov_b32 s53, 0
	s_lshl_b64 s[52:53], s[52:53], 14
	s_add_u32 s52, s52, s2
	s_addc_u32 s53, s53, s3
	global_load_dwordx4 v[72:75], v1, s[52:53]
	global_load_dwordx4 v[76:79], v1, s[52:53] offset:1024
	s_waitcnt vmcnt(0)
	s_add_i32 s55, s14, 8
	s_add_i32 s52, s55, 0
	s_mov_b32 s53, 0
	s_lshl_b64 s[52:53], s[52:53], 14
	s_add_u32 s52, s52, s2
	s_addc_u32 s53, s53, s3
	global_load_dwordx4 v[80:83], v1, s[52:53]
	global_load_dwordx4 v[84:87], v1, s[52:53] offset:1024
	s_add_i32 s52, s55, 1
	s_mov_b32 s53, 0
	s_lshl_b64 s[52:53], s[52:53], 14
	s_add_u32 s52, s52, s2
	s_addc_u32 s53, s53, s3
	global_load_dwordx4 v[88:91], v1, s[52:53]
	global_load_dwordx4 v[92:95], v1, s[52:53] offset:1024
	s_add_i32 s52, s55, 2
	s_mov_b32 s53, 0
	s_lshl_b64 s[52:53], s[52:53], 14
	s_add_u32 s52, s52, s2
	s_addc_u32 s53, s53, s3
	global_load_dwordx4 v[96:99], v1, s[52:53]
	global_load_dwordx4 v[100:103], v1, s[52:53] offset:1024
	s_add_i32 s52, s55, 3
	s_mov_b32 s53, 0
	s_lshl_b64 s[52:53], s[52:53], 14
	s_add_u32 s52, s52, s2
	s_addc_u32 s53, s53, s3
	global_load_dwordx4 v[104:107], v1, s[52:53]
	global_load_dwordx4 v[108:111], v1, s[52:53] offset:1024
	s_add_i32 s52, s55, 4
	s_mov_b32 s53, 0
	s_lshl_b64 s[52:53], s[52:53], 14
	s_add_u32 s52, s52, s2
	s_addc_u32 s53, s53, s3
	global_load_dwordx4 v[112:115], v1, s[52:53]
	global_load_dwordx4 v[116:119], v1, s[52:53] offset:1024
	s_add_i32 s52, s55, 5
	s_mov_b32 s53, 0
	s_lshl_b64 s[52:53], s[52:53], 14
	s_add_u32 s52, s52, s2
	s_addc_u32 s53, s53, s3
	global_load_dwordx4 v[120:123], v1, s[52:53]
	global_load_dwordx4 v[124:127], v1, s[52:53] offset:1024
	s_add_i32 s52, s55, 6
	s_mov_b32 s53, 0
	s_lshl_b64 s[52:53], s[52:53], 14
	s_add_u32 s52, s52, s2
	s_addc_u32 s53, s53, s3
	global_load_dwordx4 v[128:131], v1, s[52:53]
	global_load_dwordx4 v[132:135], v1, s[52:53] offset:1024
	s_add_i32 s52, s55, 7
	s_mov_b32 s53, 0
	s_lshl_b64 s[52:53], s[52:53], 14
	s_add_u32 s52, s52, s2
	s_addc_u32 s53, s53, s3
	global_load_dwordx4 v[136:139], v1, s[52:53]
	global_load_dwordx4 v[140:143], v1, s[52:53] offset:1024
	v_mul_f32_e32 v4, v16, v16
	v_fmac_f32_e32 v4, v17, v17
	v_fmac_f32_e32 v4, v18, v18
	v_fmac_f32_e32 v4, v19, v19
	v_fmac_f32_e32 v4, v20, v20
	v_fmac_f32_e32 v4, v21, v21
	v_fmac_f32_e32 v4, v22, v22
	v_fmac_f32_e32 v4, v23, v23
	v_mul_f32_e32 v5, v24, v24
	v_fmac_f32_e32 v5, v25, v25
	v_fmac_f32_e32 v5, v26, v26
	v_fmac_f32_e32 v5, v27, v27
	v_fmac_f32_e32 v5, v28, v28
	v_fmac_f32_e32 v5, v29, v29
	v_fmac_f32_e32 v5, v30, v30
	v_fmac_f32_e32 v5, v31, v31
	v_mul_f32_e32 v6, v32, v32
	v_fmac_f32_e32 v6, v33, v33
	v_fmac_f32_e32 v6, v34, v34
	v_fmac_f32_e32 v6, v35, v35
	v_fmac_f32_e32 v6, v36, v36
	v_fmac_f32_e32 v6, v37, v37
	v_fmac_f32_e32 v6, v38, v38
	v_fmac_f32_e32 v6, v39, v39
	v_mul_f32_e32 v7, v40, v40
	v_fmac_f32_e32 v7, v41, v41
	v_fmac_f32_e32 v7, v42, v42
	v_fmac_f32_e32 v7, v43, v43
	v_fmac_f32_e32 v7, v44, v44
	v_fmac_f32_e32 v7, v45, v45
	v_fmac_f32_e32 v7, v46, v46
	v_fmac_f32_e32 v7, v47, v47
	v_mul_f32_e32 v8, v48, v48
	v_fmac_f32_e32 v8, v49, v49
	v_fmac_f32_e32 v8, v50, v50
	v_fmac_f32_e32 v8, v51, v51
	v_fmac_f32_e32 v8, v52, v52
	v_fmac_f32_e32 v8, v53, v53
	v_fmac_f32_e32 v8, v54, v54
	v_fmac_f32_e32 v8, v55, v55
	v_mul_f32_e32 v9, v56, v56
	v_fmac_f32_e32 v9, v57, v57
	v_fmac_f32_e32 v9, v58, v58
	v_fmac_f32_e32 v9, v59, v59
	v_fmac_f32_e32 v9, v60, v60
	v_fmac_f32_e32 v9, v61, v61
	v_fmac_f32_e32 v9, v62, v62
	v_fmac_f32_e32 v9, v63, v63
	v_mul_f32_e32 v10, v64, v64
	v_fmac_f32_e32 v10, v65, v65
	v_fmac_f32_e32 v10, v66, v66
	v_fmac_f32_e32 v10, v67, v67
	v_fmac_f32_e32 v10, v68, v68
	v_fmac_f32_e32 v10, v69, v69
	v_fmac_f32_e32 v10, v70, v70
	v_fmac_f32_e32 v10, v71, v71
	v_mul_f32_e32 v11, v72, v72
	v_fmac_f32_e32 v11, v73, v73
	v_fmac_f32_e32 v11, v74, v74
	v_fmac_f32_e32 v11, v75, v75
	v_fmac_f32_e32 v11, v76, v76
	v_fmac_f32_e32 v11, v77, v77
	v_fmac_f32_e32 v11, v78, v78
	v_fmac_f32_e32 v11, v79, v79
	s_nop 1
	v_add_f32_dpp v4, v4, v4 quad_perm:[1,0,3,2] row_mask:0xf bank_mask:0xf bound_ctrl:1
	v_add_f32_dpp v5, v5, v5 quad_perm:[1,0,3,2] row_mask:0xf bank_mask:0xf bound_ctrl:1
	v_add_f32_dpp v6, v6, v6 quad_perm:[1,0,3,2] row_mask:0xf bank_mask:0xf bound_ctrl:1
	v_add_f32_dpp v7, v7, v7 quad_perm:[1,0,3,2] row_mask:0xf bank_mask:0xf bound_ctrl:1
	v_add_f32_dpp v8, v8, v8 quad_perm:[1,0,3,2] row_mask:0xf bank_mask:0xf bound_ctrl:1
	v_add_f32_dpp v9, v9, v9 quad_perm:[1,0,3,2] row_mask:0xf bank_mask:0xf bound_ctrl:1
	v_add_f32_dpp v10, v10, v10 quad_perm:[1,0,3,2] row_mask:0xf bank_mask:0xf bound_ctrl:1
	v_add_f32_dpp v11, v11, v11 quad_perm:[1,0,3,2] row_mask:0xf bank_mask:0xf bound_ctrl:1
	s_nop 1
	v_add_f32_dpp v4, v4, v4 quad_perm:[2,3,0,1] row_mask:0xf bank_mask:0xf bound_ctrl:1
	v_add_f32_dpp v5, v5, v5 quad_perm:[2,3,0,1] row_mask:0xf bank_mask:0xf bound_ctrl:1
	v_add_f32_dpp v6, v6, v6 quad_perm:[2,3,0,1] row_mask:0xf bank_mask:0xf bound_ctrl:1
	v_add_f32_dpp v7, v7, v7 quad_perm:[2,3,0,1] row_mask:0xf bank_mask:0xf bound_ctrl:1
	v_add_f32_dpp v8, v8, v8 quad_perm:[2,3,0,1] row_mask:0xf bank_mask:0xf bound_ctrl:1
	v_add_f32_dpp v9, v9, v9 quad_perm:[2,3,0,1] row_mask:0xf bank_mask:0xf bound_ctrl:1
	v_add_f32_dpp v10, v10, v10 quad_perm:[2,3,0,1] row_mask:0xf bank_mask:0xf bound_ctrl:1
	v_add_f32_dpp v11, v11, v11 quad_perm:[2,3,0,1] row_mask:0xf bank_mask:0xf bound_ctrl:1
	s_nop 1
	v_add_f32_dpp v4, v4, v4 row_half_mirror row_mask:0xf bank_mask:0xf bound_ctrl:1
	v_add_f32_dpp v5, v5, v5 row_half_mirror row_mask:0xf bank_mask:0xf bound_ctrl:1
	v_add_f32_dpp v6, v6, v6 row_half_mirror row_mask:0xf bank_mask:0xf bound_ctrl:1
	v_add_f32_dpp v7, v7, v7 row_half_mirror row_mask:0xf bank_mask:0xf bound_ctrl:1
	v_add_f32_dpp v8, v8, v8 row_half_mirror row_mask:0xf bank_mask:0xf bound_ctrl:1
	v_add_f32_dpp v9, v9, v9 row_half_mirror row_mask:0xf bank_mask:0xf bound_ctrl:1
	v_add_f32_dpp v10, v10, v10 row_half_mirror row_mask:0xf bank_mask:0xf bound_ctrl:1
	v_add_f32_dpp v11, v11, v11 row_half_mirror row_mask:0xf bank_mask:0xf bound_ctrl:1
	s_nop 1
	v_add_f32_dpp v4, v4, v4 row_mirror row_mask:0xf bank_mask:0xf bound_ctrl:1
	v_add_f32_dpp v5, v5, v5 row_mirror row_mask:0xf bank_mask:0xf bound_ctrl:1
	v_add_f32_dpp v6, v6, v6 row_mirror row_mask:0xf bank_mask:0xf bound_ctrl:1
	v_add_f32_dpp v7, v7, v7 row_mirror row_mask:0xf bank_mask:0xf bound_ctrl:1
	v_add_f32_dpp v8, v8, v8 row_mirror row_mask:0xf bank_mask:0xf bound_ctrl:1
	v_add_f32_dpp v9, v9, v9 row_mirror row_mask:0xf bank_mask:0xf bound_ctrl:1
	v_add_f32_dpp v10, v10, v10 row_mirror row_mask:0xf bank_mask:0xf bound_ctrl:1
	v_add_f32_dpp v11, v11, v11 row_mirror row_mask:0xf bank_mask:0xf bound_ctrl:1
	v_lshrrev_b32_e32 v217, 6, v1
	v_and_b32_e32 v217, 12, v217
	s_lshl_b32 s52, s9, 4
	s_add_i32 s52, s52, 0
	v_add_u32_e32 v217, s52, v217
	s_mov_b32 exec_lo, 0x10001
	s_mov_b32 exec_hi, 0x10001
	ds_write_b32 v217, v4
	ds_write_b32 v217, v5 offset:128
	ds_write_b32 v217, v6 offset:256
	ds_write_b32 v217, v7 offset:384
	ds_write_b32 v217, v8 offset:512
	ds_write_b32 v217, v9 offset:640
	ds_write_b32 v217, v10 offset:768
	ds_write_b32 v217, v11 offset:896
	s_mov_b64 exec, -1
	s_waitcnt lgkmcnt(0)
	s_barrier
	v_lshrrev_b32_e32 v218, 4, v1
	v_and_b32_e32 v218, 7, v218
	v_lshlrev_b32_e32 v217, 7, v218
	ds_read_b128 v[12:15], v217
	ds_read_b128 v[220:223], v217 offset:16
	s_waitcnt lgkmcnt(0)
	v_add_f32_e32 v216, v12, v13
	v_add_f32_e32 v216, v216, v14
	v_add_f32_e32 v216, v216, v15
	v_add_f32_e32 v216, v216, v220
	v_add_f32_e32 v216, v216, v221
	v_add_f32_e32 v216, v216, v222
	v_add_f32_e32 v216, v216, v223
	ds_read_b128 v[12:15], v217 offset:32
	ds_read_b128 v[220:223], v217 offset:48
	s_waitcnt lgkmcnt(0)
	v_add_f32_e32 v216, v216, v12
	v_add_f32_e32 v216, v216, v13
	v_add_f32_e32 v216, v216, v14
	v_add_f32_e32 v216, v216, v15
	v_add_f32_e32 v216, v216, v220
	v_add_f32_e32 v216, v216, v221
	v_add_f32_e32 v216, v216, v222
	v_add_f32_e32 v216, v216, v223
	ds_read_b128 v[12:15], v217 offset:64
	ds_read_b128 v[220:223], v217 offset:80
	s_waitcnt lgkmcnt(0)
	v_add_f32_e32 v216, v216, v12
	v_add_f32_e32 v216, v216, v13
	v_add_f32_e32 v216, v216, v14
	v_add_f32_e32 v216, v216, v15
	v_add_f32_e32 v216, v216, v220
	v_add_f32_e32 v216, v216, v221
	v_add_f32_e32 v216, v216, v222
	v_add_f32_e32 v216, v216, v223
	ds_read_b128 v[12:15], v217 offset:96
	ds_read_b128 v[220:223], v217 offset:112
	s_waitcnt lgkmcnt(0)
	v_add_f32_e32 v216, v216, v12
	v_add_f32_e32 v216, v216, v13
	v_add_f32_e32 v216, v216, v14
	v_add_f32_e32 v216, v216, v15
	v_add_f32_e32 v216, v216, v220
	v_add_f32_e32 v216, v216, v221
	v_add_f32_e32 v216, v216, v222
	v_add_f32_e32 v216, v216, v223
	v_mov_b32_e32 v221, 0x358637bd
	v_mov_b32_e32 v222, 0x260
	s_mov_b32 s54, 0xf800000
	v_fmamk_f32 v216, v216, 0x39800000, v221
	v_mul_f32_e32 v12, 0x4f800000, v216
	v_cmp_gt_f32_e32 vcc, s54, v216
	s_nop 1
	v_cndmask_b32_e32 v216, v216, v12, vcc
	v_sqrt_f32_e32 v12, v216
	s_nop 0
	v_add_u32_e32 v13, -1, v12
	v_add_u32_e32 v14, 1, v12
	v_fma_f32 v15, -v13, v12, v216
	v_fma_f32 v220, -v14, v12, v216
	v_cmp_ge_f32_e64 s[30:31], 0, v15
	s_nop 1
	v_cndmask_b32_e64 v12, v12, v13, s[30:31]
	v_cmp_lt_f32_e64 s[30:31], 0, v220
	s_nop 1
	v_cndmask_b32_e64 v12, v12, v14, s[30:31]
	v_mul_f32_e32 v13, 0x37800000, v12
	v_cndmask_b32_e32 v12, v12, v13, vcc
	v_cmp_class_f32_e32 vcc, v216, v222
	s_nop 1
	v_cndmask_b32_e32 v216, v12, v216, vcc
	v_div_scale_f32 v12, s[30:31], v216, v216, 1.0
	v_rcp_f32_e32 v13, v12
	v_div_scale_f32 v14, vcc, 1.0, v216, 1.0
	v_fma_f32 v15, -v12, v13, 1.0
	v_fmac_f32_e32 v13, v15, v13
	v_mul_f32_e32 v15, v14, v13
	v_fma_f32 v220, -v12, v15, v14
	v_fmac_f32_e32 v15, v220, v13
	v_fma_f32 v12, -v12, v15, v14
	v_div_fmas_f32 v12, v12, v13, v15
	v_div_fixup_f32 v216, v12, v216, 1.0
	s_mul_i32 s52, s9, 320
	s_lshl_b32 s53, s13, 5
	s_add_i32 s52, s52, s53
	s_add_i32 s52, s52, 0x800
	v_lshl_add_u32 v217, v218, 2, s52
	ds_write_b32 v217, v216
	s_lshl_b32 s53, s13, 3
	s_sub_i32 s53, 16, s53
	v_sub_u32_e32 v12, s53, v218
	v_cmp_ge_u32_e32 vcc, s12, v12
	s_nop 1
	v_cndmask_b32_e32 v216, 0, v216, vcc
	s_nop 1
	v_readlane_b32 s20, v216, 0
	v_readlane_b32 s21, v216, 1
	v_readlane_b32 s22, v216, 2
	v_readlane_b32 s23, v216, 3
	v_readlane_b32 s24, v216, 4
	v_readlane_b32 s25, v216, 5
	v_readlane_b32 s26, v216, 6
	v_readlane_b32 s27, v216, 7
	s_nop 1
	v_lshlrev_b32_e32 v217, 1, v1
	v_add_u32_e32 v217, s28, v217
	ds_read_b128 v[4:7], v217
	ds_read_b128 v[8:11], v217 offset:16
	s_waitcnt lgkmcnt(0)
	v_mul_f32_e32 v16, s20, v16
	v_mul_f32_e32 v17, s20, v17
	v_mul_f32_e32 v18, s20, v18
	v_mul_f32_e32 v19, s20, v19
	v_mul_f32_e32 v20, s20, v20
	v_mul_f32_e32 v21, s20, v21
	v_mul_f32_e32 v22, s20, v22
	v_mul_f32_e32 v23, s20, v23
	v_pk_mul_f32 v[16:17], v[16:17], v[4:5]
	v_pk_mul_f32 v[18:19], v[18:19], v[6:7]
	v_pk_mul_f32 v[20:21], v[20:21], v[8:9]
	v_pk_mul_f32 v[22:23], v[22:23], v[10:11]
	v_mul_f32_e32 v24, s21, v24
	v_mul_f32_e32 v25, s21, v25
	v_mul_f32_e32 v26, s21, v26
	v_mul_f32_e32 v27, s21, v27
	v_mul_f32_e32 v28, s21, v28
	v_mul_f32_e32 v29, s21, v29
	v_mul_f32_e32 v30, s21, v30
	v_mul_f32_e32 v31, s21, v31
	v_pk_mul_f32 v[24:25], v[24:25], v[4:5]
	v_pk_mul_f32 v[26:27], v[26:27], v[6:7]
	v_pk_mul_f32 v[28:29], v[28:29], v[8:9]
	v_pk_mul_f32 v[30:31], v[30:31], v[10:11]
	v_mul_f32_e32 v32, s22, v32
	v_mul_f32_e32 v33, s22, v33
	v_mul_f32_e32 v34, s22, v34
	v_mul_f32_e32 v35, s22, v35
	v_mul_f32_e32 v36, s22, v36
	v_mul_f32_e32 v37, s22, v37
	v_mul_f32_e32 v38, s22, v38
	v_mul_f32_e32 v39, s22, v39
	v_pk_mul_f32 v[32:33], v[32:33], v[4:5]
	v_pk_mul_f32 v[34:35], v[34:35], v[6:7]
	v_pk_mul_f32 v[36:37], v[36:37], v[8:9]
	v_pk_mul_f32 v[38:39], v[38:39], v[10:11]
	v_mul_f32_e32 v40, s23, v40
	v_mul_f32_e32 v41, s23, v41
	v_mul_f32_e32 v42, s23, v42
	v_mul_f32_e32 v43, s23, v43
	v_mul_f32_e32 v44, s23, v44
	v_mul_f32_e32 v45, s23, v45
	v_mul_f32_e32 v46, s23, v46
	v_mul_f32_e32 v47, s23, v47
	v_pk_mul_f32 v[40:41], v[40:41], v[4:5]
	v_pk_mul_f32 v[42:43], v[42:43], v[6:7]
	v_pk_mul_f32 v[44:45], v[44:45], v[8:9]
	v_pk_mul_f32 v[46:47], v[46:47], v[10:11]
	v_mul_f32_e32 v48, s24, v48
	v_mul_f32_e32 v49, s24, v49
	v_mul_f32_e32 v50, s24, v50
	v_mul_f32_e32 v51, s24, v51
	v_mul_f32_e32 v52, s24, v52
	v_mul_f32_e32 v53, s24, v53
	v_mul_f32_e32 v54, s24, v54
	v_mul_f32_e32 v55, s24, v55
	v_pk_mul_f32 v[48:49], v[48:49], v[4:5]
	v_pk_mul_f32 v[50:51], v[50:51], v[6:7]
	v_pk_mul_f32 v[52:53], v[52:53], v[8:9]
	v_pk_mul_f32 v[54:55], v[54:55], v[10:11]
	v_mul_f32_e32 v56, s25, v56
	v_mul_f32_e32 v57, s25, v57
	v_mul_f32_e32 v58, s25, v58
	v_mul_f32_e32 v59, s25, v59
	v_mul_f32_e32 v60, s25, v60
	v_mul_f32_e32 v61, s25, v61
	v_mul_f32_e32 v62, s25, v62
	v_mul_f32_e32 v63, s25, v63
	v_pk_mul_f32 v[56:57], v[56:57], v[4:5]
	v_pk_mul_f32 v[58:59], v[58:59], v[6:7]
	v_pk_mul_f32 v[60:61], v[60:61], v[8:9]
	v_pk_mul_f32 v[62:63], v[62:63], v[10:11]
	v_mul_f32_e32 v64, s26, v64
	v_mul_f32_e32 v65, s26, v65
	v_mul_f32_e32 v66, s26, v66
	v_mul_f32_e32 v67, s26, v67
	v_mul_f32_e32 v68, s26, v68
	v_mul_f32_e32 v69, s26, v69
	v_mul_f32_e32 v70, s26, v70
	v_mul_f32_e32 v71, s26, v71
	v_pk_mul_f32 v[64:65], v[64:65], v[4:5]
	v_pk_mul_f32 v[66:67], v[66:67], v[6:7]
	v_pk_mul_f32 v[68:69], v[68:69], v[8:9]
	v_pk_mul_f32 v[70:71], v[70:71], v[10:11]
	v_mul_f32_e32 v72, s27, v72
	v_mul_f32_e32 v73, s27, v73
	v_mul_f32_e32 v74, s27, v74
	v_mul_f32_e32 v75, s27, v75
	v_mul_f32_e32 v76, s27, v76
	v_mul_f32_e32 v77, s27, v77
	v_mul_f32_e32 v78, s27, v78
	v_mul_f32_e32 v79, s27, v79
	v_pk_mul_f32 v[72:73], v[72:73], v[4:5]
	v_pk_mul_f32 v[74:75], v[74:75], v[6:7]
	v_pk_mul_f32 v[76:77], v[76:77], v[8:9]
	v_pk_mul_f32 v[78:79], v[78:79], v[10:11]
	v_pk_add_f32 v[208:209], v[208:209], v[16:17]
	v_pk_add_f32 v[210:211], v[210:211], v[18:19]
	v_pk_add_f32 v[212:213], v[212:213], v[20:21]
	v_pk_add_f32 v[214:215], v[214:215], v[22:23]
	v_pk_add_f32 v[208:209], v[208:209], v[24:25]
	v_pk_add_f32 v[210:211], v[210:211], v[26:27]
	v_pk_add_f32 v[212:213], v[212:213], v[28:29]
	v_pk_add_f32 v[214:215], v[214:215], v[30:31]
	v_pk_add_f32 v[208:209], v[208:209], v[32:33]
	v_pk_add_f32 v[210:211], v[210:211], v[34:35]
	v_pk_add_f32 v[212:213], v[212:213], v[36:37]
	v_pk_add_f32 v[214:215], v[214:215], v[38:39]
	v_pk_add_f32 v[208:209], v[208:209], v[40:41]
	v_pk_add_f32 v[210:211], v[210:211], v[42:43]
	v_pk_add_f32 v[212:213], v[212:213], v[44:45]
	v_pk_add_f32 v[214:215], v[214:215], v[46:47]
	v_pk_add_f32 v[208:209], v[208:209], v[48:49]
	v_pk_add_f32 v[210:211], v[210:211], v[50:51]
	v_pk_add_f32 v[212:213], v[212:213], v[52:53]
	v_pk_add_f32 v[214:215], v[214:215], v[54:55]
	v_pk_add_f32 v[208:209], v[208:209], v[56:57]
	v_pk_add_f32 v[210:211], v[210:211], v[58:59]
	v_pk_add_f32 v[212:213], v[212:213], v[60:61]
	v_pk_add_f32 v[214:215], v[214:215], v[62:63]
	v_pk_add_f32 v[208:209], v[208:209], v[64:65]
	v_pk_add_f32 v[210:211], v[210:211], v[66:67]
	v_pk_add_f32 v[212:213], v[212:213], v[68:69]
	v_pk_add_f32 v[214:215], v[214:215], v[70:71]
	v_pk_add_f32 v[208:209], v[208:209], v[72:73]
	v_pk_add_f32 v[210:211], v[210:211], v[74:75]
	v_pk_add_f32 v[212:213], v[212:213], v[76:77]
	v_pk_add_f32 v[214:215], v[214:215], v[78:79]
	s_add_i32 s13, s13, 1
	s_add_i32 s14, s14, 8
	s_add_i32 s15, s15, 8
	s_waitcnt vmcnt(0)
	s_add_i32 s55, s14, 8
	s_add_i32 s52, s55, 0
	s_mov_b32 s53, 0
	s_lshl_b64 s[52:53], s[52:53], 14
	s_add_u32 s52, s52, s2
	s_addc_u32 s53, s53, s3
	global_load_dwordx4 v[16:19], v1, s[52:53]
	global_load_dwordx4 v[20:23], v1, s[52:53] offset:1024
	s_add_i32 s52, s55, 1
	s_mov_b32 s53, 0
	s_lshl_b64 s[52:53], s[52:53], 14
	s_add_u32 s52, s52, s2
	s_addc_u32 s53, s53, s3
	global_load_dwordx4 v[24:27], v1, s[52:53]
	global_load_dwordx4 v[28:31], v1, s[52:53] offset:1024
	s_add_i32 s52, s55, 2
	s_mov_b32 s53, 0
	s_lshl_b64 s[52:53], s[52:53], 14
	s_add_u32 s52, s52, s2
	s_addc_u32 s53, s53, s3
	global_load_dwordx4 v[32:35], v1, s[52:53]
	global_load_dwordx4 v[36:39], v1, s[52:53] offset:1024
	s_add_i32 s52, s55, 3
	s_mov_b32 s53, 0
	s_lshl_b64 s[52:53], s[52:53], 14
	s_add_u32 s52, s52, s2
	s_addc_u32 s53, s53, s3
	global_load_dwordx4 v[40:43], v1, s[52:53]
	global_load_dwordx4 v[44:47], v1, s[52:53] offset:1024
	s_add_i32 s52, s55, 4
	s_mov_b32 s53, 0
	s_lshl_b64 s[52:53], s[52:53], 14
	s_add_u32 s52, s52, s2
	s_addc_u32 s53, s53, s3
	global_load_dwordx4 v[48:51], v1, s[52:53]
	global_load_dwordx4 v[52:55], v1, s[52:53] offset:1024
	s_add_i32 s52, s55, 5
	s_mov_b32 s53, 0
	s_lshl_b64 s[52:53], s[52:53], 14
	s_add_u32 s52, s52, s2
	s_addc_u32 s53, s53, s3
	global_load_dwordx4 v[56:59], v1, s[52:53]
	global_load_dwordx4 v[60:63], v1, s[52:53] offset:1024
	s_add_i32 s52, s55, 6
	s_mov_b32 s53, 0
	s_lshl_b64 s[52:53], s[52:53], 14
	s_add_u32 s52, s52, s2
	s_addc_u32 s53, s53, s3
	global_load_dwordx4 v[64:67], v1, s[52:53]
	global_load_dwordx4 v[68:71], v1, s[52:53] offset:1024
	s_add_i32 s52, s55, 7
	s_mov_b32 s53, 0
	s_lshl_b64 s[52:53], s[52:53], 14
	s_add_u32 s52, s52, s2
	s_addc_u32 s53, s53, s3
	global_load_dwordx4 v[72:75], v1, s[52:53]
	global_load_dwordx4 v[76:79], v1, s[52:53] offset:1024
	v_mul_f32_e32 v4, v80, v80
	v_fmac_f32_e32 v4, v81, v81
	v_fmac_f32_e32 v4, v82, v82
	v_fmac_f32_e32 v4, v83, v83
	v_fmac_f32_e32 v4, v84, v84
	v_fmac_f32_e32 v4, v85, v85
	v_fmac_f32_e32 v4, v86, v86
	v_fmac_f32_e32 v4, v87, v87
	v_mul_f32_e32 v5, v88, v88
	v_fmac_f32_e32 v5, v89, v89
	v_fmac_f32_e32 v5, v90, v90
	v_fmac_f32_e32 v5, v91, v91
	v_fmac_f32_e32 v5, v92, v92
	v_fmac_f32_e32 v5, v93, v93
	v_fmac_f32_e32 v5, v94, v94
	v_fmac_f32_e32 v5, v95, v95
	v_mul_f32_e32 v6, v96, v96
	v_fmac_f32_e32 v6, v97, v97
	v_fmac_f32_e32 v6, v98, v98
	v_fmac_f32_e32 v6, v99, v99
	v_fmac_f32_e32 v6, v100, v100
	v_fmac_f32_e32 v6, v101, v101
	v_fmac_f32_e32 v6, v102, v102
	v_fmac_f32_e32 v6, v103, v103
	v_mul_f32_e32 v7, v104, v104
	v_fmac_f32_e32 v7, v105, v105
	v_fmac_f32_e32 v7, v106, v106
	v_fmac_f32_e32 v7, v107, v107
	v_fmac_f32_e32 v7, v108, v108
	v_fmac_f32_e32 v7, v109, v109
	v_fmac_f32_e32 v7, v110, v110
	v_fmac_f32_e32 v7, v111, v111
	v_mul_f32_e32 v8, v112, v112
	v_fmac_f32_e32 v8, v113, v113
	v_fmac_f32_e32 v8, v114, v114
	v_fmac_f32_e32 v8, v115, v115
	v_fmac_f32_e32 v8, v116, v116
	v_fmac_f32_e32 v8, v117, v117
	v_fmac_f32_e32 v8, v118, v118
	v_fmac_f32_e32 v8, v119, v119
	v_mul_f32_e32 v9, v120, v120
	v_fmac_f32_e32 v9, v121, v121
	v_fmac_f32_e32 v9, v122, v122
	v_fmac_f32_e32 v9, v123, v123
	v_fmac_f32_e32 v9, v124, v124
	v_fmac_f32_e32 v9, v125, v125
	v_fmac_f32_e32 v9, v126, v126
	v_fmac_f32_e32 v9, v127, v127
	v_mul_f32_e32 v10, v128, v128
	v_fmac_f32_e32 v10, v129, v129
	v_fmac_f32_e32 v10, v130, v130
	v_fmac_f32_e32 v10, v131, v131
	v_fmac_f32_e32 v10, v132, v132
	v_fmac_f32_e32 v10, v133, v133
	v_fmac_f32_e32 v10, v134, v134
	v_fmac_f32_e32 v10, v135, v135
	v_mul_f32_e32 v11, v136, v136
	v_fmac_f32_e32 v11, v137, v137
	v_fmac_f32_e32 v11, v138, v138
	v_fmac_f32_e32 v11, v139, v139
	v_fmac_f32_e32 v11, v140, v140
	v_fmac_f32_e32 v11, v141, v141
	v_fmac_f32_e32 v11, v142, v142
	v_fmac_f32_e32 v11, v143, v143
	s_nop 1
	v_add_f32_dpp v4, v4, v4 quad_perm:[1,0,3,2] row_mask:0xf bank_mask:0xf bound_ctrl:1
	v_add_f32_dpp v5, v5, v5 quad_perm:[1,0,3,2] row_mask:0xf bank_mask:0xf bound_ctrl:1
	v_add_f32_dpp v6, v6, v6 quad_perm:[1,0,3,2] row_mask:0xf bank_mask:0xf bound_ctrl:1
	v_add_f32_dpp v7, v7, v7 quad_perm:[1,0,3,2] row_mask:0xf bank_mask:0xf bound_ctrl:1
	v_add_f32_dpp v8, v8, v8 quad_perm:[1,0,3,2] row_mask:0xf bank_mask:0xf bound_ctrl:1
	v_add_f32_dpp v9, v9, v9 quad_perm:[1,0,3,2] row_mask:0xf bank_mask:0xf bound_ctrl:1
	v_add_f32_dpp v10, v10, v10 quad_perm:[1,0,3,2] row_mask:0xf bank_mask:0xf bound_ctrl:1
	v_add_f32_dpp v11, v11, v11 quad_perm:[1,0,3,2] row_mask:0xf bank_mask:0xf bound_ctrl:1
	s_nop 1
	v_add_f32_dpp v4, v4, v4 quad_perm:[2,3,0,1] row_mask:0xf bank_mask:0xf bound_ctrl:1
	v_add_f32_dpp v5, v5, v5 quad_perm:[2,3,0,1] row_mask:0xf bank_mask:0xf bound_ctrl:1
	v_add_f32_dpp v6, v6, v6 quad_perm:[2,3,0,1] row_mask:0xf bank_mask:0xf bound_ctrl:1
	v_add_f32_dpp v7, v7, v7 quad_perm:[2,3,0,1] row_mask:0xf bank_mask:0xf bound_ctrl:1
	v_add_f32_dpp v8, v8, v8 quad_perm:[2,3,0,1] row_mask:0xf bank_mask:0xf bound_ctrl:1
	v_add_f32_dpp v9, v9, v9 quad_perm:[2,3,0,1] row_mask:0xf bank_mask:0xf bound_ctrl:1
	v_add_f32_dpp v10, v10, v10 quad_perm:[2,3,0,1] row_mask:0xf bank_mask:0xf bound_ctrl:1
	v_add_f32_dpp v11, v11, v11 quad_perm:[2,3,0,1] row_mask:0xf bank_mask:0xf bound_ctrl:1
	s_nop 1
	v_add_f32_dpp v4, v4, v4 row_half_mirror row_mask:0xf bank_mask:0xf bound_ctrl:1
	v_add_f32_dpp v5, v5, v5 row_half_mirror row_mask:0xf bank_mask:0xf bound_ctrl:1
	v_add_f32_dpp v6, v6, v6 row_half_mirror row_mask:0xf bank_mask:0xf bound_ctrl:1
	v_add_f32_dpp v7, v7, v7 row_half_mirror row_mask:0xf bank_mask:0xf bound_ctrl:1
	v_add_f32_dpp v8, v8, v8 row_half_mirror row_mask:0xf bank_mask:0xf bound_ctrl:1
	v_add_f32_dpp v9, v9, v9 row_half_mirror row_mask:0xf bank_mask:0xf bound_ctrl:1
	v_add_f32_dpp v10, v10, v10 row_half_mirror row_mask:0xf bank_mask:0xf bound_ctrl:1
	v_add_f32_dpp v11, v11, v11 row_half_mirror row_mask:0xf bank_mask:0xf bound_ctrl:1
	s_nop 1
	v_add_f32_dpp v4, v4, v4 row_mirror row_mask:0xf bank_mask:0xf bound_ctrl:1
	v_add_f32_dpp v5, v5, v5 row_mirror row_mask:0xf bank_mask:0xf bound_ctrl:1
	v_add_f32_dpp v6, v6, v6 row_mirror row_mask:0xf bank_mask:0xf bound_ctrl:1
	v_add_f32_dpp v7, v7, v7 row_mirror row_mask:0xf bank_mask:0xf bound_ctrl:1
	v_add_f32_dpp v8, v8, v8 row_mirror row_mask:0xf bank_mask:0xf bound_ctrl:1
	v_add_f32_dpp v9, v9, v9 row_mirror row_mask:0xf bank_mask:0xf bound_ctrl:1
	v_add_f32_dpp v10, v10, v10 row_mirror row_mask:0xf bank_mask:0xf bound_ctrl:1
	v_add_f32_dpp v11, v11, v11 row_mirror row_mask:0xf bank_mask:0xf bound_ctrl:1
	v_lshrrev_b32_e32 v217, 6, v1
	v_and_b32_e32 v217, 12, v217
	s_lshl_b32 s52, s9, 4
	s_add_i32 s52, s52, 1024
	v_add_u32_e32 v217, s52, v217
	s_mov_b32 exec_lo, 0x10001
	s_mov_b32 exec_hi, 0x10001
	ds_write_b32 v217, v4
	ds_write_b32 v217, v5 offset:128
	ds_write_b32 v217, v6 offset:256
	ds_write_b32 v217, v7 offset:384
	ds_write_b32 v217, v8 offset:512
	ds_write_b32 v217, v9 offset:640
	ds_write_b32 v217, v10 offset:768
	ds_write_b32 v217, v11 offset:896
	s_mov_b64 exec, -1
	s_waitcnt lgkmcnt(0)
	s_barrier
	v_lshrrev_b32_e32 v218, 4, v1
	v_and_b32_e32 v218, 7, v218
	v_lshlrev_b32_e32 v217, 7, v218
	v_add_u32_e32 v217, 0x400, v217
	ds_read_b128 v[12:15], v217
	ds_read_b128 v[220:223], v217 offset:16
	s_waitcnt lgkmcnt(0)
	v_add_f32_e32 v216, v12, v13
	v_add_f32_e32 v216, v216, v14
	v_add_f32_e32 v216, v216, v15
	v_add_f32_e32 v216, v216, v220
	v_add_f32_e32 v216, v216, v221
	v_add_f32_e32 v216, v216, v222
	v_add_f32_e32 v216, v216, v223
	ds_read_b128 v[12:15], v217 offset:32
	ds_read_b128 v[220:223], v217 offset:48
	s_waitcnt lgkmcnt(0)
	v_add_f32_e32 v216, v216, v12
	v_add_f32_e32 v216, v216, v13
	v_add_f32_e32 v216, v216, v14
	v_add_f32_e32 v216, v216, v15
	v_add_f32_e32 v216, v216, v220
	v_add_f32_e32 v216, v216, v221
	v_add_f32_e32 v216, v216, v222
	v_add_f32_e32 v216, v216, v223
	ds_read_b128 v[12:15], v217 offset:64
	ds_read_b128 v[220:223], v217 offset:80
	s_waitcnt lgkmcnt(0)
	v_add_f32_e32 v216, v216, v12
	v_add_f32_e32 v216, v216, v13
	v_add_f32_e32 v216, v216, v14
	v_add_f32_e32 v216, v216, v15
	v_add_f32_e32 v216, v216, v220
	v_add_f32_e32 v216, v216, v221
	v_add_f32_e32 v216, v216, v222
	v_add_f32_e32 v216, v216, v223
	ds_read_b128 v[12:15], v217 offset:96
	ds_read_b128 v[220:223], v217 offset:112
	s_waitcnt lgkmcnt(0)
	v_add_f32_e32 v216, v216, v12
	v_add_f32_e32 v216, v216, v13
	v_add_f32_e32 v216, v216, v14
	v_add_f32_e32 v216, v216, v15
	v_add_f32_e32 v216, v216, v220
	v_add_f32_e32 v216, v216, v221
	v_add_f32_e32 v216, v216, v222
	v_add_f32_e32 v216, v216, v223
	v_mov_b32_e32 v221, 0x358637bd
	v_mov_b32_e32 v222, 0x260
	s_mov_b32 s54, 0xf800000
	v_fmamk_f32 v216, v216, 0x39800000, v221
	v_mul_f32_e32 v12, 0x4f800000, v216
	v_cmp_gt_f32_e32 vcc, s54, v216
	s_nop 1
	v_cndmask_b32_e32 v216, v216, v12, vcc
	v_sqrt_f32_e32 v12, v216
	s_nop 0
	v_add_u32_e32 v13, -1, v12
	v_add_u32_e32 v14, 1, v12
	v_fma_f32 v15, -v13, v12, v216
	v_fma_f32 v220, -v14, v12, v216
	v_cmp_ge_f32_e64 s[30:31], 0, v15
	s_nop 1
	v_cndmask_b32_e64 v12, v12, v13, s[30:31]
	v_cmp_lt_f32_e64 s[30:31], 0, v220
	s_nop 1
	v_cndmask_b32_e64 v12, v12, v14, s[30:31]
	v_mul_f32_e32 v13, 0x37800000, v12
	v_cndmask_b32_e32 v12, v12, v13, vcc
	v_cmp_class_f32_e32 vcc, v216, v222
	s_nop 1
	v_cndmask_b32_e32 v216, v12, v216, vcc
	v_div_scale_f32 v12, s[30:31], v216, v216, 1.0
	v_rcp_f32_e32 v13, v12
	v_div_scale_f32 v14, vcc, 1.0, v216, 1.0
	v_fma_f32 v15, -v12, v13, 1.0
	v_fmac_f32_e32 v13, v15, v13
	v_mul_f32_e32 v15, v14, v13
	v_fma_f32 v220, -v12, v15, v14
	v_fmac_f32_e32 v15, v220, v13
	v_fma_f32 v12, -v12, v15, v14
	v_div_fmas_f32 v12, v12, v13, v15
	v_div_fixup_f32 v216, v12, v216, 1.0
	s_mul_i32 s52, s9, 320
	s_lshl_b32 s53, s13, 5
	s_add_i32 s52, s52, s53
	s_add_i32 s52, s52, 0x800
	v_lshl_add_u32 v217, v218, 2, s52
	ds_write_b32 v217, v216
	s_lshl_b32 s53, s13, 3
	s_sub_i32 s53, 16, s53
	v_sub_u32_e32 v12, s53, v218
	v_cmp_ge_u32_e32 vcc, s12, v12
	s_nop 1
	v_cndmask_b32_e32 v216, 0, v216, vcc
	s_nop 1
	v_readlane_b32 s20, v216, 0
	v_readlane_b32 s21, v216, 1
	v_readlane_b32 s22, v216, 2
	v_readlane_b32 s23, v216, 3
	v_readlane_b32 s24, v216, 4
	v_readlane_b32 s25, v216, 5
	v_readlane_b32 s26, v216, 6
	v_readlane_b32 s27, v216, 7
	s_nop 1
	v_lshlrev_b32_e32 v217, 1, v1
	v_add_u32_e32 v217, s28, v217
	ds_read_b128 v[4:7], v217
	ds_read_b128 v[8:11], v217 offset:16
	s_waitcnt lgkmcnt(0)
	v_mul_f32_e32 v80, s20, v80
	v_mul_f32_e32 v81, s20, v81
	v_mul_f32_e32 v82, s20, v82
	v_mul_f32_e32 v83, s20, v83
	v_mul_f32_e32 v84, s20, v84
	v_mul_f32_e32 v85, s20, v85
	v_mul_f32_e32 v86, s20, v86
	v_mul_f32_e32 v87, s20, v87
	v_pk_mul_f32 v[80:81], v[80:81], v[4:5]
	v_pk_mul_f32 v[82:83], v[82:83], v[6:7]
	v_pk_mul_f32 v[84:85], v[84:85], v[8:9]
	v_pk_mul_f32 v[86:87], v[86:87], v[10:11]
	v_mul_f32_e32 v88, s21, v88
	v_mul_f32_e32 v89, s21, v89
	v_mul_f32_e32 v90, s21, v90
	v_mul_f32_e32 v91, s21, v91
	v_mul_f32_e32 v92, s21, v92
	v_mul_f32_e32 v93, s21, v93
	v_mul_f32_e32 v94, s21, v94
	v_mul_f32_e32 v95, s21, v95
	v_pk_mul_f32 v[88:89], v[88:89], v[4:5]
	v_pk_mul_f32 v[90:91], v[90:91], v[6:7]
	v_pk_mul_f32 v[92:93], v[92:93], v[8:9]
	v_pk_mul_f32 v[94:95], v[94:95], v[10:11]
	v_mul_f32_e32 v96, s22, v96
	v_mul_f32_e32 v97, s22, v97
	v_mul_f32_e32 v98, s22, v98
	v_mul_f32_e32 v99, s22, v99
	v_mul_f32_e32 v100, s22, v100
	v_mul_f32_e32 v101, s22, v101
	v_mul_f32_e32 v102, s22, v102
	v_mul_f32_e32 v103, s22, v103
	v_pk_mul_f32 v[96:97], v[96:97], v[4:5]
	v_pk_mul_f32 v[98:99], v[98:99], v[6:7]
	v_pk_mul_f32 v[100:101], v[100:101], v[8:9]
	v_pk_mul_f32 v[102:103], v[102:103], v[10:11]
	v_mul_f32_e32 v104, s23, v104
	v_mul_f32_e32 v105, s23, v105
	v_mul_f32_e32 v106, s23, v106
	v_mul_f32_e32 v107, s23, v107
	v_mul_f32_e32 v108, s23, v108
	v_mul_f32_e32 v109, s23, v109
	v_mul_f32_e32 v110, s23, v110
	v_mul_f32_e32 v111, s23, v111
	v_pk_mul_f32 v[104:105], v[104:105], v[4:5]
	v_pk_mul_f32 v[106:107], v[106:107], v[6:7]
	v_pk_mul_f32 v[108:109], v[108:109], v[8:9]
	v_pk_mul_f32 v[110:111], v[110:111], v[10:11]
	v_mul_f32_e32 v112, s24, v112
	v_mul_f32_e32 v113, s24, v113
	v_mul_f32_e32 v114, s24, v114
	v_mul_f32_e32 v115, s24, v115
	v_mul_f32_e32 v116, s24, v116
	v_mul_f32_e32 v117, s24, v117
	v_mul_f32_e32 v118, s24, v118
	v_mul_f32_e32 v119, s24, v119
	v_pk_mul_f32 v[112:113], v[112:113], v[4:5]
	v_pk_mul_f32 v[114:115], v[114:115], v[6:7]
	v_pk_mul_f32 v[116:117], v[116:117], v[8:9]
	v_pk_mul_f32 v[118:119], v[118:119], v[10:11]
	v_mul_f32_e32 v120, s25, v120
	v_mul_f32_e32 v121, s25, v121
	v_mul_f32_e32 v122, s25, v122
	v_mul_f32_e32 v123, s25, v123
	v_mul_f32_e32 v124, s25, v124
	v_mul_f32_e32 v125, s25, v125
	v_mul_f32_e32 v126, s25, v126
	v_mul_f32_e32 v127, s25, v127
	v_pk_mul_f32 v[120:121], v[120:121], v[4:5]
	v_pk_mul_f32 v[122:123], v[122:123], v[6:7]
	v_pk_mul_f32 v[124:125], v[124:125], v[8:9]
	v_pk_mul_f32 v[126:127], v[126:127], v[10:11]
	v_mul_f32_e32 v128, s26, v128
	v_mul_f32_e32 v129, s26, v129
	v_mul_f32_e32 v130, s26, v130
	v_mul_f32_e32 v131, s26, v131
	v_mul_f32_e32 v132, s26, v132
	v_mul_f32_e32 v133, s26, v133
	v_mul_f32_e32 v134, s26, v134
	v_mul_f32_e32 v135, s26, v135
	v_pk_mul_f32 v[128:129], v[128:129], v[4:5]
	v_pk_mul_f32 v[130:131], v[130:131], v[6:7]
	v_pk_mul_f32 v[132:133], v[132:133], v[8:9]
	v_pk_mul_f32 v[134:135], v[134:135], v[10:11]
	v_mul_f32_e32 v136, s27, v136
	v_mul_f32_e32 v137, s27, v137
	v_mul_f32_e32 v138, s27, v138
	v_mul_f32_e32 v139, s27, v139
	v_mul_f32_e32 v140, s27, v140
	v_mul_f32_e32 v141, s27, v141
	v_mul_f32_e32 v142, s27, v142
	v_mul_f32_e32 v143, s27, v143
	v_pk_mul_f32 v[136:137], v[136:137], v[4:5]
	v_pk_mul_f32 v[138:139], v[138:139], v[6:7]
	v_pk_mul_f32 v[140:141], v[140:141], v[8:9]
	v_pk_mul_f32 v[142:143], v[142:143], v[10:11]
	v_pk_add_f32 v[208:209], v[208:209], v[80:81]
	v_pk_add_f32 v[210:211], v[210:211], v[82:83]
	v_pk_add_f32 v[212:213], v[212:213], v[84:85]
	v_pk_add_f32 v[214:215], v[214:215], v[86:87]
	v_pk_add_f32 v[208:209], v[208:209], v[88:89]
	v_pk_add_f32 v[210:211], v[210:211], v[90:91]
	v_pk_add_f32 v[212:213], v[212:213], v[92:93]
	v_pk_add_f32 v[214:215], v[214:215], v[94:95]
	v_pk_add_f32 v[208:209], v[208:209], v[96:97]
	v_pk_add_f32 v[210:211], v[210:211], v[98:99]
	v_pk_add_f32 v[212:213], v[212:213], v[100:101]
	v_pk_add_f32 v[214:215], v[214:215], v[102:103]
	v_pk_add_f32 v[208:209], v[208:209], v[104:105]
	v_pk_add_f32 v[210:211], v[210:211], v[106:107]
	v_pk_add_f32 v[212:213], v[212:213], v[108:109]
	v_pk_add_f32 v[214:215], v[214:215], v[110:111]
	v_pk_add_f32 v[208:209], v[208:209], v[112:113]
	v_pk_add_f32 v[210:211], v[210:211], v[114:115]
	v_pk_add_f32 v[212:213], v[212:213], v[116:117]
	v_pk_add_f32 v[214:215], v[214:215], v[118:119]
	v_pk_add_f32 v[208:209], v[208:209], v[120:121]
	v_pk_add_f32 v[210:211], v[210:211], v[122:123]
	v_pk_add_f32 v[212:213], v[212:213], v[124:125]
	v_pk_add_f32 v[214:215], v[214:215], v[126:127]
	v_pk_add_f32 v[208:209], v[208:209], v[128:129]
	v_pk_add_f32 v[210:211], v[210:211], v[130:131]
	v_pk_add_f32 v[212:213], v[212:213], v[132:133]
	v_pk_add_f32 v[214:215], v[214:215], v[134:135]
	v_pk_add_f32 v[208:209], v[208:209], v[136:137]
	v_pk_add_f32 v[210:211], v[210:211], v[138:139]
	v_pk_add_f32 v[212:213], v[212:213], v[140:141]
	v_pk_add_f32 v[214:215], v[214:215], v[142:143]
	s_add_i32 s13, s13, 1
	s_add_i32 s14, s14, 8
	s_add_i32 s15, s15, 8
	s_branch .Lp1f_main

.Lp1f_loop:
	s_waitcnt vmcnt(16)
	s_add_i32 s52, s14, 0
	s_sub_i32 s52, s52, s12
	s_max_i32 s52, s52, 0
	s_mov_b32 s53, 0
	s_lshl_b64 s[52:53], s[52:53], 14
	s_add_u32 s52, s52, s2
	s_addc_u32 s53, s53, s3
	global_load_dwordx4 v[144:147], v1, s[52:53]
	global_load_dwordx4 v[148:151], v1, s[52:53] offset:1024
	s_add_i32 s52, s14, 1
	s_sub_i32 s52, s52, s12
	s_max_i32 s52, s52, 0
	s_mov_b32 s53, 0
	s_lshl_b64 s[52:53], s[52:53], 14
	s_add_u32 s52, s52, s2
	s_addc_u32 s53, s53, s3
	global_load_dwordx4 v[152:155], v1, s[52:53]
	global_load_dwordx4 v[156:159], v1, s[52:53] offset:1024
	s_add_i32 s52, s14, 2
	s_sub_i32 s52, s52, s12
	s_max_i32 s52, s52, 0
	s_mov_b32 s53, 0
	s_lshl_b64 s[52:53], s[52:53], 14
	s_add_u32 s52, s52, s2
	s_addc_u32 s53, s53, s3
	global_load_dwordx4 v[160:163], v1, s[52:53]
	global_load_dwordx4 v[164:167], v1, s[52:53] offset:1024
	s_add_i32 s52, s14, 3
	s_sub_i32 s52, s52, s12
	s_max_i32 s52, s52, 0
	s_mov_b32 s53, 0
	s_lshl_b64 s[52:53], s[52:53], 14
	s_add_u32 s52, s52, s2
	s_addc_u32 s53, s53, s3
	global_load_dwordx4 v[168:171], v1, s[52:53]
	global_load_dwordx4 v[172:175], v1, s[52:53] offset:1024
	s_add_i32 s52, s14, 4
	s_sub_i32 s52, s52, s12
	s_max_i32 s52, s52, 0
	s_mov_b32 s53, 0
	s_lshl_b64 s[52:53], s[52:53], 14
	s_add_u32 s52, s52, s2
	s_addc_u32 s53, s53, s3
	global_load_dwordx4 v[176:179], v1, s[52:53]
	global_load_dwordx4 v[180:183], v1, s[52:53] offset:1024
	s_add_i32 s52, s14, 5
	s_sub_i32 s52, s52, s12
	s_max_i32 s52, s52, 0
	s_mov_b32 s53, 0
	s_lshl_b64 s[52:53], s[52:53], 14
	s_add_u32 s52, s52, s2
	s_addc_u32 s53, s53, s3
	global_load_dwordx4 v[184:187], v1, s[52:53]
	global_load_dwordx4 v[188:191], v1, s[52:53] offset:1024
	s_add_i32 s52, s14, 6
	s_sub_i32 s52, s52, s12
	s_max_i32 s52, s52, 0
	s_mov_b32 s53, 0
	s_lshl_b64 s[52:53], s[52:53], 14
	s_add_u32 s52, s52, s2
	s_addc_u32 s53, s53, s3
	global_load_dwordx4 v[192:195], v1, s[52:53]
	global_load_dwordx4 v[196:199], v1, s[52:53] offset:1024
	s_add_i32 s52, s14, 7
	s_sub_i32 s52, s52, s12
	s_max_i32 s52, s52, 0
	s_mov_b32 s53, 0
	s_lshl_b64 s[52:53], s[52:53], 14
	s_add_u32 s52, s52, s2
	s_addc_u32 s53, s53, s3
	global_load_dwordx4 v[200:203], v1, s[52:53]
	global_load_dwordx4 v[204:207], v1, s[52:53] offset:1024
	s_cmp_ge_u32 s13, 9
	s_cbranch_scc1 .Lp1f_nonext_m0
	s_add_i32 s55, s14, 8
	s_add_i32 s52, s55, 0
	s_mov_b32 s53, 0
	s_lshl_b64 s[52:53], s[52:53], 14
	s_add_u32 s52, s52, s2
	s_addc_u32 s53, s53, s3
	global_load_dwordx4 v[80:83], v1, s[52:53]
	global_load_dwordx4 v[84:87], v1, s[52:53] offset:1024
	s_add_i32 s52, s55, 1
	s_mov_b32 s53, 0
	s_lshl_b64 s[52:53], s[52:53], 14
	s_add_u32 s52, s52, s2
	s_addc_u32 s53, s53, s3
	global_load_dwordx4 v[88:91], v1, s[52:53]
	global_load_dwordx4 v[92:95], v1, s[52:53] offset:1024
	s_add_i32 s52, s55, 2
	s_mov_b32 s53, 0
	s_lshl_b64 s[52:53], s[52:53], 14
	s_add_u32 s52, s52, s2
	s_addc_u32 s53, s53, s3
	global_load_dwordx4 v[96:99], v1, s[52:53]
	global_load_dwordx4 v[100:103], v1, s[52:53] offset:1024
	s_add_i32 s52, s55, 3
	s_mov_b32 s53, 0
	s_lshl_b64 s[52:53], s[52:53], 14
	s_add_u32 s52, s52, s2
	s_addc_u32 s53, s53, s3
	global_load_dwordx4 v[104:107], v1, s[52:53]
	global_load_dwordx4 v[108:111], v1, s[52:53] offset:1024
	s_add_i32 s52, s55, 4
	s_mov_b32 s53, 0
	s_lshl_b64 s[52:53], s[52:53], 14
	s_add_u32 s52, s52, s2
	s_addc_u32 s53, s53, s3
	global_load_dwordx4 v[112:115], v1, s[52:53]
	global_load_dwordx4 v[116:119], v1, s[52:53] offset:1024
	s_add_i32 s52, s55, 5
	s_mov_b32 s53, 0
	s_lshl_b64 s[52:53], s[52:53], 14
	s_add_u32 s52, s52, s2
	s_addc_u32 s53, s53, s3
	global_load_dwordx4 v[120:123], v1, s[52:53]
	global_load_dwordx4 v[124:127], v1, s[52:53] offset:1024
	s_add_i32 s52, s55, 6
	s_mov_b32 s53, 0
	s_lshl_b64 s[52:53], s[52:53], 14
	s_add_u32 s52, s52, s2
	s_addc_u32 s53, s53, s3
	global_load_dwordx4 v[128:131], v1, s[52:53]
	global_load_dwordx4 v[132:135], v1, s[52:53] offset:1024
	s_add_i32 s52, s55, 7
	s_mov_b32 s53, 0
	s_lshl_b64 s[52:53], s[52:53], 14
	s_add_u32 s52, s52, s2
	s_addc_u32 s53, s53, s3
	global_load_dwordx4 v[136:139], v1, s[52:53]
	global_load_dwordx4 v[140:143], v1, s[52:53] offset:1024
.Lp1f_nonext_m0:
	v_mul_f32_e32 v4, v16, v16
	v_fmac_f32_e32 v4, v17, v17
	v_fmac_f32_e32 v4, v18, v18
	v_fmac_f32_e32 v4, v19, v19
	v_fmac_f32_e32 v4, v20, v20
	v_fmac_f32_e32 v4, v21, v21
	v_fmac_f32_e32 v4, v22, v22
	v_fmac_f32_e32 v4, v23, v23
	v_mul_f32_e32 v5, v24, v24
	v_fmac_f32_e32 v5, v25, v25
	v_fmac_f32_e32 v5, v26, v26
	v_fmac_f32_e32 v5, v27, v27
	v_fmac_f32_e32 v5, v28, v28
	v_fmac_f32_e32 v5, v29, v29
	v_fmac_f32_e32 v5, v30, v30
	v_fmac_f32_e32 v5, v31, v31
	v_mul_f32_e32 v6, v32, v32
	v_fmac_f32_e32 v6, v33, v33
	v_fmac_f32_e32 v6, v34, v34
	v_fmac_f32_e32 v6, v35, v35
	v_fmac_f32_e32 v6, v36, v36
	v_fmac_f32_e32 v6, v37, v37
	v_fmac_f32_e32 v6, v38, v38
	v_fmac_f32_e32 v6, v39, v39
	v_mul_f32_e32 v7, v40, v40
	v_fmac_f32_e32 v7, v41, v41
	v_fmac_f32_e32 v7, v42, v42
	v_fmac_f32_e32 v7, v43, v43
	v_fmac_f32_e32 v7, v44, v44
	v_fmac_f32_e32 v7, v45, v45
	v_fmac_f32_e32 v7, v46, v46
	v_fmac_f32_e32 v7, v47, v47
	v_mul_f32_e32 v8, v48, v48
	v_fmac_f32_e32 v8, v49, v49
	v_fmac_f32_e32 v8, v50, v50
	v_fmac_f32_e32 v8, v51, v51
	v_fmac_f32_e32 v8, v52, v52
	v_fmac_f32_e32 v8, v53, v53
	v_fmac_f32_e32 v8, v54, v54
	v_fmac_f32_e32 v8, v55, v55
	v_mul_f32_e32 v9, v56, v56
	v_fmac_f32_e32 v9, v57, v57
	v_fmac_f32_e32 v9, v58, v58
	v_fmac_f32_e32 v9, v59, v59
	v_fmac_f32_e32 v9, v60, v60
	v_fmac_f32_e32 v9, v61, v61
	v_fmac_f32_e32 v9, v62, v62
	v_fmac_f32_e32 v9, v63, v63
	v_mul_f32_e32 v10, v64, v64
	v_fmac_f32_e32 v10, v65, v65
	v_fmac_f32_e32 v10, v66, v66
	v_fmac_f32_e32 v10, v67, v67
	v_fmac_f32_e32 v10, v68, v68
	v_fmac_f32_e32 v10, v69, v69
	v_fmac_f32_e32 v10, v70, v70
	v_fmac_f32_e32 v10, v71, v71
	v_mul_f32_e32 v11, v72, v72
	v_fmac_f32_e32 v11, v73, v73
	v_fmac_f32_e32 v11, v74, v74
	v_fmac_f32_e32 v11, v75, v75
	v_fmac_f32_e32 v11, v76, v76
	v_fmac_f32_e32 v11, v77, v77
	v_fmac_f32_e32 v11, v78, v78
	v_fmac_f32_e32 v11, v79, v79
	s_nop 1
	v_add_f32_dpp v4, v4, v4 quad_perm:[1,0,3,2] row_mask:0xf bank_mask:0xf bound_ctrl:1
	v_add_f32_dpp v5, v5, v5 quad_perm:[1,0,3,2] row_mask:0xf bank_mask:0xf bound_ctrl:1
	v_add_f32_dpp v6, v6, v6 quad_perm:[1,0,3,2] row_mask:0xf bank_mask:0xf bound_ctrl:1
	v_add_f32_dpp v7, v7, v7 quad_perm:[1,0,3,2] row_mask:0xf bank_mask:0xf bound_ctrl:1
	v_add_f32_dpp v8, v8, v8 quad_perm:[1,0,3,2] row_mask:0xf bank_mask:0xf bound_ctrl:1
	v_add_f32_dpp v9, v9, v9 quad_perm:[1,0,3,2] row_mask:0xf bank_mask:0xf bound_ctrl:1
	v_add_f32_dpp v10, v10, v10 quad_perm:[1,0,3,2] row_mask:0xf bank_mask:0xf bound_ctrl:1
	v_add_f32_dpp v11, v11, v11 quad_perm:[1,0,3,2] row_mask:0xf bank_mask:0xf bound_ctrl:1
	s_nop 1
	v_add_f32_dpp v4, v4, v4 quad_perm:[2,3,0,1] row_mask:0xf bank_mask:0xf bound_ctrl:1
	v_add_f32_dpp v5, v5, v5 quad_perm:[2,3,0,1] row_mask:0xf bank_mask:0xf bound_ctrl:1
	v_add_f32_dpp v6, v6, v6 quad_perm:[2,3,0,1] row_mask:0xf bank_mask:0xf bound_ctrl:1
	v_add_f32_dpp v7, v7, v7 quad_perm:[2,3,0,1] row_mask:0xf bank_mask:0xf bound_ctrl:1
	v_add_f32_dpp v8, v8, v8 quad_perm:[2,3,0,1] row_mask:0xf bank_mask:0xf bound_ctrl:1
	v_add_f32_dpp v9, v9, v9 quad_perm:[2,3,0,1] row_mask:0xf bank_mask:0xf bound_ctrl:1
	v_add_f32_dpp v10, v10, v10 quad_perm:[2,3,0,1] row_mask:0xf bank_mask:0xf bound_ctrl:1
	v_add_f32_dpp v11, v11, v11 quad_perm:[2,3,0,1] row_mask:0xf bank_mask:0xf bound_ctrl:1
	s_nop 1
	v_add_f32_dpp v4, v4, v4 row_half_mirror row_mask:0xf bank_mask:0xf bound_ctrl:1
	v_add_f32_dpp v5, v5, v5 row_half_mirror row_mask:0xf bank_mask:0xf bound_ctrl:1
	v_add_f32_dpp v6, v6, v6 row_half_mirror row_mask:0xf bank_mask:0xf bound_ctrl:1
	v_add_f32_dpp v7, v7, v7 row_half_mirror row_mask:0xf bank_mask:0xf bound_ctrl:1
	v_add_f32_dpp v8, v8, v8 row_half_mirror row_mask:0xf bank_mask:0xf bound_ctrl:1
	v_add_f32_dpp v9, v9, v9 row_half_mirror row_mask:0xf bank_mask:0xf bound_ctrl:1
	v_add_f32_dpp v10, v10, v10 row_half_mirror row_mask:0xf bank_mask:0xf bound_ctrl:1
	v_add_f32_dpp v11, v11, v11 row_half_mirror row_mask:0xf bank_mask:0xf bound_ctrl:1
	s_nop 1
	v_add_f32_dpp v4, v4, v4 row_mirror row_mask:0xf bank_mask:0xf bound_ctrl:1
	v_add_f32_dpp v5, v5, v5 row_mirror row_mask:0xf bank_mask:0xf bound_ctrl:1
	v_add_f32_dpp v6, v6, v6 row_mirror row_mask:0xf bank_mask:0xf bound_ctrl:1
	v_add_f32_dpp v7, v7, v7 row_mirror row_mask:0xf bank_mask:0xf bound_ctrl:1
	v_add_f32_dpp v8, v8, v8 row_mirror row_mask:0xf bank_mask:0xf bound_ctrl:1
	v_add_f32_dpp v9, v9, v9 row_mirror row_mask:0xf bank_mask:0xf bound_ctrl:1
	v_add_f32_dpp v10, v10, v10 row_mirror row_mask:0xf bank_mask:0xf bound_ctrl:1
	v_add_f32_dpp v11, v11, v11 row_mirror row_mask:0xf bank_mask:0xf bound_ctrl:1
	v_lshrrev_b32_e32 v217, 6, v1
	v_and_b32_e32 v217, 12, v217
	s_lshl_b32 s52, s9, 4
	s_add_i32 s52, s52, 0
	v_add_u32_e32 v217, s52, v217
	s_mov_b32 exec_lo, 0x10001
	s_mov_b32 exec_hi, 0x10001
	ds_write_b32 v217, v4
	ds_write_b32 v217, v5 offset:128
	ds_write_b32 v217, v6 offset:256
	ds_write_b32 v217, v7 offset:384
	ds_write_b32 v217, v8 offset:512
	ds_write_b32 v217, v9 offset:640
	ds_write_b32 v217, v10 offset:768
	ds_write_b32 v217, v11 offset:896
	s_mov_b64 exec, -1
	s_waitcnt lgkmcnt(0)
	s_barrier
	v_lshrrev_b32_e32 v218, 4, v1
	v_and_b32_e32 v218, 7, v218
	v_lshlrev_b32_e32 v217, 7, v218
	ds_read_b128 v[12:15], v217
	ds_read_b128 v[220:223], v217 offset:16
	s_waitcnt lgkmcnt(0)
	v_add_f32_e32 v216, v12, v13
	v_add_f32_e32 v216, v216, v14
	v_add_f32_e32 v216, v216, v15
	v_add_f32_e32 v216, v216, v220
	v_add_f32_e32 v216, v216, v221
	v_add_f32_e32 v216, v216, v222
	v_add_f32_e32 v216, v216, v223
	ds_read_b128 v[12:15], v217 offset:32
	ds_read_b128 v[220:223], v217 offset:48
	s_waitcnt lgkmcnt(0)
	v_add_f32_e32 v216, v216, v12
	v_add_f32_e32 v216, v216, v13
	v_add_f32_e32 v216, v216, v14
	v_add_f32_e32 v216, v216, v15
	v_add_f32_e32 v216, v216, v220
	v_add_f32_e32 v216, v216, v221
	v_add_f32_e32 v216, v216, v222
	v_add_f32_e32 v216, v216, v223
	ds_read_b128 v[12:15], v217 offset:64
	ds_read_b128 v[220:223], v217 offset:80
	s_waitcnt lgkmcnt(0)
	v_add_f32_e32 v216, v216, v12
	v_add_f32_e32 v216, v216, v13
	v_add_f32_e32 v216, v216, v14
	v_add_f32_e32 v216, v216, v15
	v_add_f32_e32 v216, v216, v220
	v_add_f32_e32 v216, v216, v221
	v_add_f32_e32 v216, v216, v222
	v_add_f32_e32 v216, v216, v223
	ds_read_b128 v[12:15], v217 offset:96
	ds_read_b128 v[220:223], v217 offset:112
	s_waitcnt lgkmcnt(0)
	v_add_f32_e32 v216, v216, v12
	v_add_f32_e32 v216, v216, v13
	v_add_f32_e32 v216, v216, v14
	v_add_f32_e32 v216, v216, v15
	v_add_f32_e32 v216, v216, v220
	v_add_f32_e32 v216, v216, v221
	v_add_f32_e32 v216, v216, v222
	v_add_f32_e32 v216, v216, v223
	v_mov_b32_e32 v221, 0x358637bd
	v_mov_b32_e32 v222, 0x260
	s_mov_b32 s54, 0xf800000
	v_fmamk_f32 v216, v216, 0x39800000, v221
	v_mul_f32_e32 v12, 0x4f800000, v216
	v_cmp_gt_f32_e32 vcc, s54, v216
	s_nop 1
	v_cndmask_b32_e32 v216, v216, v12, vcc
	v_sqrt_f32_e32 v12, v216
	s_nop 0
	v_add_u32_e32 v13, -1, v12
	v_add_u32_e32 v14, 1, v12
	v_fma_f32 v15, -v13, v12, v216
	v_fma_f32 v220, -v14, v12, v216
	v_cmp_ge_f32_e64 s[30:31], 0, v15
	s_nop 1
	v_cndmask_b32_e64 v12, v12, v13, s[30:31]
	v_cmp_lt_f32_e64 s[30:31], 0, v220
	s_nop 1
	v_cndmask_b32_e64 v12, v12, v14, s[30:31]
	v_mul_f32_e32 v13, 0x37800000, v12
	v_cndmask_b32_e32 v12, v12, v13, vcc
	v_cmp_class_f32_e32 vcc, v216, v222
	s_nop 1
	v_cndmask_b32_e32 v216, v12, v216, vcc
	v_div_scale_f32 v12, s[30:31], v216, v216, 1.0
	v_rcp_f32_e32 v13, v12
	v_div_scale_f32 v14, vcc, 1.0, v216, 1.0
	v_fma_f32 v15, -v12, v13, 1.0
	v_fmac_f32_e32 v13, v15, v13
	v_mul_f32_e32 v15, v14, v13
	v_fma_f32 v220, -v12, v15, v14
	v_fmac_f32_e32 v15, v220, v13
	v_fma_f32 v12, -v12, v15, v14
	v_div_fmas_f32 v12, v12, v13, v15
	v_div_fixup_f32 v216, v12, v216, 1.0
	s_mul_i32 s52, s9, 320
	s_lshl_b32 s53, s13, 5
	s_add_i32 s52, s52, s53
	s_add_i32 s52, s52, 0x800
	v_lshl_add_u32 v217, v218, 2, s52
	ds_write_b32 v217, v216
	s_nop 1
	v_readlane_b32 s20, v216, 0
	v_readlane_b32 s21, v216, 1
	v_readlane_b32 s22, v216, 2
	v_readlane_b32 s23, v216, 3
	v_readlane_b32 s24, v216, 4
	v_readlane_b32 s25, v216, 5
	v_readlane_b32 s26, v216, 6
	v_readlane_b32 s27, v216, 7
	s_lshl_b32 s53, s12, 2
	v_subrev_u32_e32 v13, s53, v217
	ds_read_b32 v14, v13
	v_add_u32_e32 v15, s15, v218
	v_cmp_le_u32_e32 vcc, s12, v15
	v_add_u32_e32 v15, 1, v15
	v_min_u32_e32 v15, s12, v15
	v_cvt_f32_u32_e32 v220, v15
	s_waitcnt lgkmcnt(0)
	v_cndmask_b32_e32 v14, 0, v14, vcc
	s_nop 1
	v_readlane_b32 s36, v14, 0
	v_readlane_b32 s37, v14, 1
	v_readlane_b32 s38, v14, 2
	v_readlane_b32 s39, v14, 3
	v_readlane_b32 s40, v14, 4
	v_readlane_b32 s41, v14, 5
	v_readlane_b32 s42, v14, 6
	v_readlane_b32 s43, v14, 7
	v_div_scale_f32 v12, s[30:31], v220, v220, 1.0
	v_rcp_f32_e32 v13, v12
	v_div_scale_f32 v14, vcc, 1.0, v220, 1.0
	v_fma_f32 v15, -v12, v13, 1.0
	v_fmac_f32_e32 v13, v15, v13
	v_mul_f32_e32 v15, v14, v13
	v_fma_f32 v221, -v12, v15, v14
	v_fmac_f32_e32 v15, v221, v13
	v_fma_f32 v12, -v12, v15, v14
	v_div_fmas_f32 v12, v12, v13, v15
	v_div_fixup_f32 v216, v12, v220, 1.0
	s_nop 1
	v_readlane_b32 s44, v216, 0
	v_readlane_b32 s45, v216, 1
	v_readlane_b32 s46, v216, 2
	v_readlane_b32 s47, v216, 3
	v_readlane_b32 s48, v216, 4
	v_readlane_b32 s49, v216, 5
	v_readlane_b32 s50, v216, 6
	v_readlane_b32 s51, v216, 7
	s_nop 1
	v_lshlrev_b32_e32 v217, 1, v1
	v_add_u32_e32 v217, s28, v217
	ds_read_b128 v[4:7], v217
	ds_read_b128 v[8:11], v217 offset:16
	s_waitcnt lgkmcnt(0)
	v_mul_f32_e32 v16, s20, v16
	v_mul_f32_e32 v17, s20, v17
	v_mul_f32_e32 v18, s20, v18
	v_mul_f32_e32 v19, s20, v19
	v_mul_f32_e32 v20, s20, v20
	v_mul_f32_e32 v21, s20, v21
	v_mul_f32_e32 v22, s20, v22
	v_mul_f32_e32 v23, s20, v23
	v_pk_mul_f32 v[16:17], v[16:17], v[4:5]
	v_pk_mul_f32 v[18:19], v[18:19], v[6:7]
	v_pk_mul_f32 v[20:21], v[20:21], v[8:9]
	v_pk_mul_f32 v[22:23], v[22:23], v[10:11]
	v_mul_f32_e32 v24, s21, v24
	v_mul_f32_e32 v25, s21, v25
	v_mul_f32_e32 v26, s21, v26
	v_mul_f32_e32 v27, s21, v27
	v_mul_f32_e32 v28, s21, v28
	v_mul_f32_e32 v29, s21, v29
	v_mul_f32_e32 v30, s21, v30
	v_mul_f32_e32 v31, s21, v31
	v_pk_mul_f32 v[24:25], v[24:25], v[4:5]
	v_pk_mul_f32 v[26:27], v[26:27], v[6:7]
	v_pk_mul_f32 v[28:29], v[28:29], v[8:9]
	v_pk_mul_f32 v[30:31], v[30:31], v[10:11]
	v_mul_f32_e32 v32, s22, v32
	v_mul_f32_e32 v33, s22, v33
	v_mul_f32_e32 v34, s22, v34
	v_mul_f32_e32 v35, s22, v35
	v_mul_f32_e32 v36, s22, v36
	v_mul_f32_e32 v37, s22, v37
	v_mul_f32_e32 v38, s22, v38
	v_mul_f32_e32 v39, s22, v39
	v_pk_mul_f32 v[32:33], v[32:33], v[4:5]
	v_pk_mul_f32 v[34:35], v[34:35], v[6:7]
	v_pk_mul_f32 v[36:37], v[36:37], v[8:9]
	v_pk_mul_f32 v[38:39], v[38:39], v[10:11]
	v_mul_f32_e32 v40, s23, v40
	v_mul_f32_e32 v41, s23, v41
	v_mul_f32_e32 v42, s23, v42
	v_mul_f32_e32 v43, s23, v43
	v_mul_f32_e32 v44, s23, v44
	v_mul_f32_e32 v45, s23, v45
	v_mul_f32_e32 v46, s23, v46
	v_mul_f32_e32 v47, s23, v47
	v_pk_mul_f32 v[40:41], v[40:41], v[4:5]
	v_pk_mul_f32 v[42:43], v[42:43], v[6:7]
	v_pk_mul_f32 v[44:45], v[44:45], v[8:9]
	v_pk_mul_f32 v[46:47], v[46:47], v[10:11]
	v_mul_f32_e32 v48, s24, v48
	v_mul_f32_e32 v49, s24, v49
	v_mul_f32_e32 v50, s24, v50
	v_mul_f32_e32 v51, s24, v51
	v_mul_f32_e32 v52, s24, v52
	v_mul_f32_e32 v53, s24, v53
	v_mul_f32_e32 v54, s24, v54
	v_mul_f32_e32 v55, s24, v55
	v_pk_mul_f32 v[48:49], v[48:49], v[4:5]
	v_pk_mul_f32 v[50:51], v[50:51], v[6:7]
	v_pk_mul_f32 v[52:53], v[52:53], v[8:9]
	v_pk_mul_f32 v[54:55], v[54:55], v[10:11]
	v_mul_f32_e32 v56, s25, v56
	v_mul_f32_e32 v57, s25, v57
	v_mul_f32_e32 v58, s25, v58
	v_mul_f32_e32 v59, s25, v59
	v_mul_f32_e32 v60, s25, v60
	v_mul_f32_e32 v61, s25, v61
	v_mul_f32_e32 v62, s25, v62
	v_mul_f32_e32 v63, s25, v63
	v_pk_mul_f32 v[56:57], v[56:57], v[4:5]
	v_pk_mul_f32 v[58:59], v[58:59], v[6:7]
	v_pk_mul_f32 v[60:61], v[60:61], v[8:9]
	v_pk_mul_f32 v[62:63], v[62:63], v[10:11]
	v_mul_f32_e32 v64, s26, v64
	v_mul_f32_e32 v65, s26, v65
	v_mul_f32_e32 v66, s26, v66
	v_mul_f32_e32 v67, s26, v67
	v_mul_f32_e32 v68, s26, v68
	v_mul_f32_e32 v69, s26, v69
	v_mul_f32_e32 v70, s26, v70
	v_mul_f32_e32 v71, s26, v71
	v_pk_mul_f32 v[64:65], v[64:65], v[4:5]
	v_pk_mul_f32 v[66:67], v[66:67], v[6:7]
	v_pk_mul_f32 v[68:69], v[68:69], v[8:9]
	v_pk_mul_f32 v[70:71], v[70:71], v[10:11]
	v_mul_f32_e32 v72, s27, v72
	v_mul_f32_e32 v73, s27, v73
	v_mul_f32_e32 v74, s27, v74
	v_mul_f32_e32 v75, s27, v75
	v_mul_f32_e32 v76, s27, v76
	v_mul_f32_e32 v77, s27, v77
	v_mul_f32_e32 v78, s27, v78
	v_mul_f32_e32 v79, s27, v79
	v_pk_mul_f32 v[72:73], v[72:73], v[4:5]
	v_pk_mul_f32 v[74:75], v[74:75], v[6:7]
	v_pk_mul_f32 v[76:77], v[76:77], v[8:9]
	v_pk_mul_f32 v[78:79], v[78:79], v[10:11]
	s_cmp_ge_u32 s13, 9
	s_cbranch_scc1 .Lp1f_w0_m0
	s_waitcnt vmcnt(16)
	s_branch .Lp1f_w1_m0

.Lp1f_w1_m0:
	v_mul_f32_e32 v144, s36, v144
	v_mul_f32_e32 v145, s36, v145
	v_mul_f32_e32 v146, s36, v146
	v_mul_f32_e32 v147, s36, v147
	v_mul_f32_e32 v148, s36, v148
	v_mul_f32_e32 v149, s36, v149
	v_mul_f32_e32 v150, s36, v150
	v_mul_f32_e32 v151, s36, v151
	v_pk_mul_f32 v[144:145], v[144:145], v[4:5]
	v_pk_mul_f32 v[146:147], v[146:147], v[6:7]
	v_pk_mul_f32 v[148:149], v[148:149], v[8:9]
	v_pk_mul_f32 v[150:151], v[150:151], v[10:11]
	v_mul_f32_e32 v152, s37, v152
	v_mul_f32_e32 v153, s37, v153
	v_mul_f32_e32 v154, s37, v154
	v_mul_f32_e32 v155, s37, v155
	v_mul_f32_e32 v156, s37, v156
	v_mul_f32_e32 v157, s37, v157
	v_mul_f32_e32 v158, s37, v158
	v_mul_f32_e32 v159, s37, v159
	v_pk_mul_f32 v[152:153], v[152:153], v[4:5]
	v_pk_mul_f32 v[154:155], v[154:155], v[6:7]
	v_pk_mul_f32 v[156:157], v[156:157], v[8:9]
	v_pk_mul_f32 v[158:159], v[158:159], v[10:11]
	v_mul_f32_e32 v160, s38, v160
	v_mul_f32_e32 v161, s38, v161
	v_mul_f32_e32 v162, s38, v162
	v_mul_f32_e32 v163, s38, v163
	v_mul_f32_e32 v164, s38, v164
	v_mul_f32_e32 v165, s38, v165
	v_mul_f32_e32 v166, s38, v166
	v_mul_f32_e32 v167, s38, v167
	v_pk_mul_f32 v[160:161], v[160:161], v[4:5]
	v_pk_mul_f32 v[162:163], v[162:163], v[6:7]
	v_pk_mul_f32 v[164:165], v[164:165], v[8:9]
	v_pk_mul_f32 v[166:167], v[166:167], v[10:11]
	v_mul_f32_e32 v168, s39, v168
	v_mul_f32_e32 v169, s39, v169
	v_mul_f32_e32 v170, s39, v170
	v_mul_f32_e32 v171, s39, v171
	v_mul_f32_e32 v172, s39, v172
	v_mul_f32_e32 v173, s39, v173
	v_mul_f32_e32 v174, s39, v174
	v_mul_f32_e32 v175, s39, v175
	v_pk_mul_f32 v[168:169], v[168:169], v[4:5]
	v_pk_mul_f32 v[170:171], v[170:171], v[6:7]
	v_pk_mul_f32 v[172:173], v[172:173], v[8:9]
	v_pk_mul_f32 v[174:175], v[174:175], v[10:11]
	v_mul_f32_e32 v176, s40, v176
	v_mul_f32_e32 v177, s40, v177
	v_mul_f32_e32 v178, s40, v178
	v_mul_f32_e32 v179, s40, v179
	v_mul_f32_e32 v180, s40, v180
	v_mul_f32_e32 v181, s40, v181
	v_mul_f32_e32 v182, s40, v182
	v_mul_f32_e32 v183, s40, v183
	v_pk_mul_f32 v[176:177], v[176:177], v[4:5]
	v_pk_mul_f32 v[178:179], v[178:179], v[6:7]
	v_pk_mul_f32 v[180:181], v[180:181], v[8:9]
	v_pk_mul_f32 v[182:183], v[182:183], v[10:11]
	v_mul_f32_e32 v184, s41, v184
	v_mul_f32_e32 v185, s41, v185
	v_mul_f32_e32 v186, s41, v186
	v_mul_f32_e32 v187, s41, v187
	v_mul_f32_e32 v188, s41, v188
	v_mul_f32_e32 v189, s41, v189
	v_mul_f32_e32 v190, s41, v190
	v_mul_f32_e32 v191, s41, v191
	v_pk_mul_f32 v[184:185], v[184:185], v[4:5]
	v_pk_mul_f32 v[186:187], v[186:187], v[6:7]
	v_pk_mul_f32 v[188:189], v[188:189], v[8:9]
	v_pk_mul_f32 v[190:191], v[190:191], v[10:11]
	v_mul_f32_e32 v192, s42, v192
	v_mul_f32_e32 v193, s42, v193
	v_mul_f32_e32 v194, s42, v194
	v_mul_f32_e32 v195, s42, v195
	v_mul_f32_e32 v196, s42, v196
	v_mul_f32_e32 v197, s42, v197
	v_mul_f32_e32 v198, s42, v198
	v_mul_f32_e32 v199, s42, v199
	v_pk_mul_f32 v[192:193], v[192:193], v[4:5]
	v_pk_mul_f32 v[194:195], v[194:195], v[6:7]
	v_pk_mul_f32 v[196:197], v[196:197], v[8:9]
	v_pk_mul_f32 v[198:199], v[198:199], v[10:11]
	v_mul_f32_e32 v200, s43, v200
	v_mul_f32_e32 v201, s43, v201
	v_mul_f32_e32 v202, s43, v202
	v_mul_f32_e32 v203, s43, v203
	v_mul_f32_e32 v204, s43, v204
	v_mul_f32_e32 v205, s43, v205
	v_mul_f32_e32 v206, s43, v206
	v_mul_f32_e32 v207, s43, v207
	v_pk_mul_f32 v[200:201], v[200:201], v[4:5]
	v_pk_mul_f32 v[202:203], v[202:203], v[6:7]
	v_pk_mul_f32 v[204:205], v[204:205], v[8:9]
	v_pk_mul_f32 v[206:207], v[206:207], v[10:11]
	v_pk_add_f32 v[208:209], v[208:209], v[16:17]
	v_pk_add_f32 v[210:211], v[210:211], v[18:19]
	v_pk_add_f32 v[212:213], v[212:213], v[20:21]
	v_pk_add_f32 v[214:215], v[214:215], v[22:23]
	v_pk_add_f32 v[208:209], v[208:209], v[144:145] neg_lo:[0,1] neg_hi:[0,1]
	v_pk_add_f32 v[210:211], v[210:211], v[146:147] neg_lo:[0,1] neg_hi:[0,1]
	v_pk_add_f32 v[212:213], v[212:213], v[148:149] neg_lo:[0,1] neg_hi:[0,1]
	v_pk_add_f32 v[214:215], v[214:215], v[150:151] neg_lo:[0,1] neg_hi:[0,1]
	v_fma_f32 v217, v208, s44, -v16
	v_fma_f32 v218, v209, s44, -v17
	v_fma_f32 v216, v210, s44, -v18
	v_fma_f32 v12, v211, s44, -v19
	v_fma_f32 v13, v212, s44, -v20
	v_fma_f32 v14, v213, s44, -v21
	v_fma_f32 v15, v214, s44, -v22
	v_fma_f32 v220, v215, s44, -v23
	v_cvt_pk_bf16_f32 v144, v217, v218
	v_cvt_pk_bf16_f32 v145, v216, v12
	v_cvt_pk_bf16_f32 v146, v13, v14
	v_cvt_pk_bf16_f32 v147, v15, v220
	s_add_i32 s52, s14, 0
	s_mov_b32 s53, 0
	s_lshl_b64 s[52:53], s[52:53], 13
	s_add_u32 s52, s52, s4
	s_addc_u32 s53, s53, s5
	global_store_dwordx2 v3, v[144:145], s[52:53]
	global_store_dwordx2 v3, v[146:147], s[52:53] offset:512
	v_pk_add_f32 v[208:209], v[208:209], v[24:25]
	v_pk_add_f32 v[210:211], v[210:211], v[26:27]
	v_pk_add_f32 v[212:213], v[212:213], v[28:29]
	v_pk_add_f32 v[214:215], v[214:215], v[30:31]
	v_pk_add_f32 v[208:209], v[208:209], v[152:153] neg_lo:[0,1] neg_hi:[0,1]
	v_pk_add_f32 v[210:211], v[210:211], v[154:155] neg_lo:[0,1] neg_hi:[0,1]
	v_pk_add_f32 v[212:213], v[212:213], v[156:157] neg_lo:[0,1] neg_hi:[0,1]
	v_pk_add_f32 v[214:215], v[214:215], v[158:159] neg_lo:[0,1] neg_hi:[0,1]
	v_fma_f32 v217, v208, s45, -v24
	v_fma_f32 v218, v209, s45, -v25
	v_fma_f32 v216, v210, s45, -v26
	v_fma_f32 v12, v211, s45, -v27
	v_fma_f32 v13, v212, s45, -v28
	v_fma_f32 v14, v213, s45, -v29
	v_fma_f32 v15, v214, s45, -v30
	v_fma_f32 v220, v215, s45, -v31
	v_cvt_pk_bf16_f32 v152, v217, v218
	v_cvt_pk_bf16_f32 v153, v216, v12
	v_cvt_pk_bf16_f32 v154, v13, v14
	v_cvt_pk_bf16_f32 v155, v15, v220
	s_add_i32 s52, s14, 1
	s_mov_b32 s53, 0
	s_lshl_b64 s[52:53], s[52:53], 13
	s_add_u32 s52, s52, s4
	s_addc_u32 s53, s53, s5
	global_store_dwordx2 v3, v[152:153], s[52:53]
	global_store_dwordx2 v3, v[154:155], s[52:53] offset:512
	v_pk_add_f32 v[208:209], v[208:209], v[32:33]
	v_pk_add_f32 v[210:211], v[210:211], v[34:35]
	v_pk_add_f32 v[212:213], v[212:213], v[36:37]
	v_pk_add_f32 v[214:215], v[214:215], v[38:39]
	v_pk_add_f32 v[208:209], v[208:209], v[160:161] neg_lo:[0,1] neg_hi:[0,1]
	v_pk_add_f32 v[210:211], v[210:211], v[162:163] neg_lo:[0,1] neg_hi:[0,1]
	v_pk_add_f32 v[212:213], v[212:213], v[164:165] neg_lo:[0,1] neg_hi:[0,1]
	v_pk_add_f32 v[214:215], v[214:215], v[166:167] neg_lo:[0,1] neg_hi:[0,1]
	v_fma_f32 v217, v208, s46, -v32
	v_fma_f32 v218, v209, s46, -v33
	v_fma_f32 v216, v210, s46, -v34
	v_fma_f32 v12, v211, s46, -v35
	v_fma_f32 v13, v212, s46, -v36
	v_fma_f32 v14, v213, s46, -v37
	v_fma_f32 v15, v214, s46, -v38
	v_fma_f32 v220, v215, s46, -v39
	v_cvt_pk_bf16_f32 v160, v217, v218
	v_cvt_pk_bf16_f32 v161, v216, v12
	v_cvt_pk_bf16_f32 v162, v13, v14
	v_cvt_pk_bf16_f32 v163, v15, v220
	s_add_i32 s52, s14, 2
	s_mov_b32 s53, 0
	s_lshl_b64 s[52:53], s[52:53], 13
	s_add_u32 s52, s52, s4
	s_addc_u32 s53, s53, s5
	global_store_dwordx2 v3, v[160:161], s[52:53]
	global_store_dwordx2 v3, v[162:163], s[52:53] offset:512
	v_pk_add_f32 v[208:209], v[208:209], v[40:41]
	v_pk_add_f32 v[210:211], v[210:211], v[42:43]
	v_pk_add_f32 v[212:213], v[212:213], v[44:45]
	v_pk_add_f32 v[214:215], v[214:215], v[46:47]
	v_pk_add_f32 v[208:209], v[208:209], v[168:169] neg_lo:[0,1] neg_hi:[0,1]
	v_pk_add_f32 v[210:211], v[210:211], v[170:171] neg_lo:[0,1] neg_hi:[0,1]
	v_pk_add_f32 v[212:213], v[212:213], v[172:173] neg_lo:[0,1] neg_hi:[0,1]
	v_pk_add_f32 v[214:215], v[214:215], v[174:175] neg_lo:[0,1] neg_hi:[0,1]
	v_fma_f32 v217, v208, s47, -v40
	v_fma_f32 v218, v209, s47, -v41
	v_fma_f32 v216, v210, s47, -v42
	v_fma_f32 v12, v211, s47, -v43
	v_fma_f32 v13, v212, s47, -v44
	v_fma_f32 v14, v213, s47, -v45
	v_fma_f32 v15, v214, s47, -v46
	v_fma_f32 v220, v215, s47, -v47
	v_cvt_pk_bf16_f32 v168, v217, v218
	v_cvt_pk_bf16_f32 v169, v216, v12
	v_cvt_pk_bf16_f32 v170, v13, v14
	v_cvt_pk_bf16_f32 v171, v15, v220
	s_add_i32 s52, s14, 3
	s_mov_b32 s53, 0
	s_lshl_b64 s[52:53], s[52:53], 13
	s_add_u32 s52, s52, s4
	s_addc_u32 s53, s53, s5
	global_store_dwordx2 v3, v[168:169], s[52:53]
	global_store_dwordx2 v3, v[170:171], s[52:53] offset:512
	v_pk_add_f32 v[208:209], v[208:209], v[48:49]
	v_pk_add_f32 v[210:211], v[210:211], v[50:51]
	v_pk_add_f32 v[212:213], v[212:213], v[52:53]
	v_pk_add_f32 v[214:215], v[214:215], v[54:55]
	v_pk_add_f32 v[208:209], v[208:209], v[176:177] neg_lo:[0,1] neg_hi:[0,1]
	v_pk_add_f32 v[210:211], v[210:211], v[178:179] neg_lo:[0,1] neg_hi:[0,1]
	v_pk_add_f32 v[212:213], v[212:213], v[180:181] neg_lo:[0,1] neg_hi:[0,1]
	v_pk_add_f32 v[214:215], v[214:215], v[182:183] neg_lo:[0,1] neg_hi:[0,1]
	v_fma_f32 v217, v208, s48, -v48
	v_fma_f32 v218, v209, s48, -v49
	v_fma_f32 v216, v210, s48, -v50
	v_fma_f32 v12, v211, s48, -v51
	v_fma_f32 v13, v212, s48, -v52
	v_fma_f32 v14, v213, s48, -v53
	v_fma_f32 v15, v214, s48, -v54
	v_fma_f32 v220, v215, s48, -v55
	v_cvt_pk_bf16_f32 v176, v217, v218
	v_cvt_pk_bf16_f32 v177, v216, v12
	v_cvt_pk_bf16_f32 v178, v13, v14
	v_cvt_pk_bf16_f32 v179, v15, v220
	s_add_i32 s52, s14, 4
	s_mov_b32 s53, 0
	s_lshl_b64 s[52:53], s[52:53], 13
	s_add_u32 s52, s52, s4
	s_addc_u32 s53, s53, s5
	global_store_dwordx2 v3, v[176:177], s[52:53]
	global_store_dwordx2 v3, v[178:179], s[52:53] offset:512
	v_pk_add_f32 v[208:209], v[208:209], v[56:57]
	v_pk_add_f32 v[210:211], v[210:211], v[58:59]
	v_pk_add_f32 v[212:213], v[212:213], v[60:61]
	v_pk_add_f32 v[214:215], v[214:215], v[62:63]
	v_pk_add_f32 v[208:209], v[208:209], v[184:185] neg_lo:[0,1] neg_hi:[0,1]
	v_pk_add_f32 v[210:211], v[210:211], v[186:187] neg_lo:[0,1] neg_hi:[0,1]
	v_pk_add_f32 v[212:213], v[212:213], v[188:189] neg_lo:[0,1] neg_hi:[0,1]
	v_pk_add_f32 v[214:215], v[214:215], v[190:191] neg_lo:[0,1] neg_hi:[0,1]
	v_fma_f32 v217, v208, s49, -v56
	v_fma_f32 v218, v209, s49, -v57
	v_fma_f32 v216, v210, s49, -v58
	v_fma_f32 v12, v211, s49, -v59
	v_fma_f32 v13, v212, s49, -v60
	v_fma_f32 v14, v213, s49, -v61
	v_fma_f32 v15, v214, s49, -v62
	v_fma_f32 v220, v215, s49, -v63
	v_cvt_pk_bf16_f32 v184, v217, v218
	v_cvt_pk_bf16_f32 v185, v216, v12
	v_cvt_pk_bf16_f32 v186, v13, v14
	v_cvt_pk_bf16_f32 v187, v15, v220
	s_add_i32 s52, s14, 5
	s_mov_b32 s53, 0
	s_lshl_b64 s[52:53], s[52:53], 13
	s_add_u32 s52, s52, s4
	s_addc_u32 s53, s53, s5
	global_store_dwordx2 v3, v[184:185], s[52:53]
	global_store_dwordx2 v3, v[186:187], s[52:53] offset:512
	v_pk_add_f32 v[208:209], v[208:209], v[64:65]
	v_pk_add_f32 v[210:211], v[210:211], v[66:67]
	v_pk_add_f32 v[212:213], v[212:213], v[68:69]
	v_pk_add_f32 v[214:215], v[214:215], v[70:71]
	v_pk_add_f32 v[208:209], v[208:209], v[192:193] neg_lo:[0,1] neg_hi:[0,1]
	v_pk_add_f32 v[210:211], v[210:211], v[194:195] neg_lo:[0,1] neg_hi:[0,1]
	v_pk_add_f32 v[212:213], v[212:213], v[196:197] neg_lo:[0,1] neg_hi:[0,1]
	v_pk_add_f32 v[214:215], v[214:215], v[198:199] neg_lo:[0,1] neg_hi:[0,1]
	v_fma_f32 v217, v208, s50, -v64
	v_fma_f32 v218, v209, s50, -v65
	v_fma_f32 v216, v210, s50, -v66
	v_fma_f32 v12, v211, s50, -v67
	v_fma_f32 v13, v212, s50, -v68
	v_fma_f32 v14, v213, s50, -v69
	v_fma_f32 v15, v214, s50, -v70
	v_fma_f32 v220, v215, s50, -v71
	v_cvt_pk_bf16_f32 v192, v217, v218
	v_cvt_pk_bf16_f32 v193, v216, v12
	v_cvt_pk_bf16_f32 v194, v13, v14
	v_cvt_pk_bf16_f32 v195, v15, v220
	s_add_i32 s52, s14, 6
	s_mov_b32 s53, 0
	s_lshl_b64 s[52:53], s[52:53], 13
	s_add_u32 s52, s52, s4
	s_addc_u32 s53, s53, s5
	global_store_dwordx2 v3, v[192:193], s[52:53]
	global_store_dwordx2 v3, v[194:195], s[52:53] offset:512
	v_pk_add_f32 v[208:209], v[208:209], v[72:73]
	v_pk_add_f32 v[210:211], v[210:211], v[74:75]
	v_pk_add_f32 v[212:213], v[212:213], v[76:77]
	v_pk_add_f32 v[214:215], v[214:215], v[78:79]
	v_pk_add_f32 v[208:209], v[208:209], v[200:201] neg_lo:[0,1] neg_hi:[0,1]
	v_pk_add_f32 v[210:211], v[210:211], v[202:203] neg_lo:[0,1] neg_hi:[0,1]
	v_pk_add_f32 v[212:213], v[212:213], v[204:205] neg_lo:[0,1] neg_hi:[0,1]
	v_pk_add_f32 v[214:215], v[214:215], v[206:207] neg_lo:[0,1] neg_hi:[0,1]
	v_fma_f32 v217, v208, s51, -v72
	v_fma_f32 v218, v209, s51, -v73
	v_fma_f32 v216, v210, s51, -v74
	v_fma_f32 v12, v211, s51, -v75
	v_fma_f32 v13, v212, s51, -v76
	v_fma_f32 v14, v213, s51, -v77
	v_fma_f32 v15, v214, s51, -v78
	v_fma_f32 v220, v215, s51, -v79
	v_cvt_pk_bf16_f32 v200, v217, v218
	v_cvt_pk_bf16_f32 v201, v216, v12
	v_cvt_pk_bf16_f32 v202, v13, v14
	v_cvt_pk_bf16_f32 v203, v15, v220
	s_add_i32 s52, s14, 7
	s_mov_b32 s53, 0
	s_lshl_b64 s[52:53], s[52:53], 13
	s_add_u32 s52, s52, s4
	s_addc_u32 s53, s53, s5
	global_store_dwordx2 v3, v[200:201], s[52:53]
	global_store_dwordx2 v3, v[202:203], s[52:53] offset:512
	s_add_i32 s13, s13, 1
	s_add_i32 s14, s14, 8
	s_add_i32 s15, s15, 8
	s_waitcnt vmcnt(16)
	s_add_i32 s52, s14, 0
	s_sub_i32 s52, s52, s12
	s_max_i32 s52, s52, 0
	s_mov_b32 s53, 0
	s_lshl_b64 s[52:53], s[52:53], 14
	s_add_u32 s52, s52, s2
	s_addc_u32 s53, s53, s3
	global_load_dwordx4 v[144:147], v1, s[52:53]
	global_load_dwordx4 v[148:151], v1, s[52:53] offset:1024
	s_add_i32 s52, s14, 1
	s_sub_i32 s52, s52, s12
	s_max_i32 s52, s52, 0
	s_mov_b32 s53, 0
	s_lshl_b64 s[52:53], s[52:53], 14
	s_add_u32 s52, s52, s2
	s_addc_u32 s53, s53, s3
	global_load_dwordx4 v[152:155], v1, s[52:53]
	global_load_dwordx4 v[156:159], v1, s[52:53] offset:1024
	s_add_i32 s52, s14, 2
	s_sub_i32 s52, s52, s12
	s_max_i32 s52, s52, 0
	s_mov_b32 s53, 0
	s_lshl_b64 s[52:53], s[52:53], 14
	s_add_u32 s52, s52, s2
	s_addc_u32 s53, s53, s3
	global_load_dwordx4 v[160:163], v1, s[52:53]
	global_load_dwordx4 v[164:167], v1, s[52:53] offset:1024
	s_add_i32 s52, s14, 3
	s_sub_i32 s52, s52, s12
	s_max_i32 s52, s52, 0
	s_mov_b32 s53, 0
	s_lshl_b64 s[52:53], s[52:53], 14
	s_add_u32 s52, s52, s2
	s_addc_u32 s53, s53, s3
	global_load_dwordx4 v[168:171], v1, s[52:53]
	global_load_dwordx4 v[172:175], v1, s[52:53] offset:1024
	s_add_i32 s52, s14, 4
	s_sub_i32 s52, s52, s12
	s_max_i32 s52, s52, 0
	s_mov_b32 s53, 0
	s_lshl_b64 s[52:53], s[52:53], 14
	s_add_u32 s52, s52, s2
	s_addc_u32 s53, s53, s3
	global_load_dwordx4 v[176:179], v1, s[52:53]
	global_load_dwordx4 v[180:183], v1, s[52:53] offset:1024
	s_add_i32 s52, s14, 5
	s_sub_i32 s52, s52, s12
	s_max_i32 s52, s52, 0
	s_mov_b32 s53, 0
	s_lshl_b64 s[52:53], s[52:53], 14
	s_add_u32 s52, s52, s2
	s_addc_u32 s53, s53, s3
	global_load_dwordx4 v[184:187], v1, s[52:53]
	global_load_dwordx4 v[188:191], v1, s[52:53] offset:1024
	s_add_i32 s52, s14, 6
	s_sub_i32 s52, s52, s12
	s_max_i32 s52, s52, 0
	s_mov_b32 s53, 0
	s_lshl_b64 s[52:53], s[52:53], 14
	s_add_u32 s52, s52, s2
	s_addc_u32 s53, s53, s3
	global_load_dwordx4 v[192:195], v1, s[52:53]
	global_load_dwordx4 v[196:199], v1, s[52:53] offset:1024
	s_add_i32 s52, s14, 7
	s_sub_i32 s52, s52, s12
	s_max_i32 s52, s52, 0
	s_mov_b32 s53, 0
	s_lshl_b64 s[52:53], s[52:53], 14
	s_add_u32 s52, s52, s2
	s_addc_u32 s53, s53, s3
	global_load_dwordx4 v[200:203], v1, s[52:53]
	global_load_dwordx4 v[204:207], v1, s[52:53] offset:1024
	s_cmp_ge_u32 s13, 9
	s_cbranch_scc1 .Lp1f_nonext_m1
	s_add_i32 s55, s14, 8
	s_add_i32 s52, s55, 0
	s_mov_b32 s53, 0
	s_lshl_b64 s[52:53], s[52:53], 14
	s_add_u32 s52, s52, s2
	s_addc_u32 s53, s53, s3
	global_load_dwordx4 v[16:19], v1, s[52:53]
	global_load_dwordx4 v[20:23], v1, s[52:53] offset:1024
	s_add_i32 s52, s55, 1
	s_mov_b32 s53, 0
	s_lshl_b64 s[52:53], s[52:53], 14
	s_add_u32 s52, s52, s2
	s_addc_u32 s53, s53, s3
	global_load_dwordx4 v[24:27], v1, s[52:53]
	global_load_dwordx4 v[28:31], v1, s[52:53] offset:1024
	s_add_i32 s52, s55, 2
	s_mov_b32 s53, 0
	s_lshl_b64 s[52:53], s[52:53], 14
	s_add_u32 s52, s52, s2
	s_addc_u32 s53, s53, s3
	global_load_dwordx4 v[32:35], v1, s[52:53]
	global_load_dwordx4 v[36:39], v1, s[52:53] offset:1024
	s_add_i32 s52, s55, 3
	s_mov_b32 s53, 0
	s_lshl_b64 s[52:53], s[52:53], 14
	s_add_u32 s52, s52, s2
	s_addc_u32 s53, s53, s3
	global_load_dwordx4 v[40:43], v1, s[52:53]
	global_load_dwordx4 v[44:47], v1, s[52:53] offset:1024
	s_add_i32 s52, s55, 4
	s_mov_b32 s53, 0
	s_lshl_b64 s[52:53], s[52:53], 14
	s_add_u32 s52, s52, s2
	s_addc_u32 s53, s53, s3
	global_load_dwordx4 v[48:51], v1, s[52:53]
	global_load_dwordx4 v[52:55], v1, s[52:53] offset:1024
	s_add_i32 s52, s55, 5
	s_mov_b32 s53, 0
	s_lshl_b64 s[52:53], s[52:53], 14
	s_add_u32 s52, s52, s2
	s_addc_u32 s53, s53, s3
	global_load_dwordx4 v[56:59], v1, s[52:53]
	global_load_dwordx4 v[60:63], v1, s[52:53] offset:1024
	s_add_i32 s52, s55, 6
	s_mov_b32 s53, 0
	s_lshl_b64 s[52:53], s[52:53], 14
	s_add_u32 s52, s52, s2
	s_addc_u32 s53, s53, s3
	global_load_dwordx4 v[64:67], v1, s[52:53]
	global_load_dwordx4 v[68:71], v1, s[52:53] offset:1024
	s_add_i32 s52, s55, 7
	s_mov_b32 s53, 0
	s_lshl_b64 s[52:53], s[52:53], 14
	s_add_u32 s52, s52, s2
	s_addc_u32 s53, s53, s3
	global_load_dwordx4 v[72:75], v1, s[52:53]
	global_load_dwordx4 v[76:79], v1, s[52:53] offset:1024
.Lp1f_nonext_m1:
	v_mul_f32_e32 v4, v80, v80
	v_fmac_f32_e32 v4, v81, v81
	v_fmac_f32_e32 v4, v82, v82
	v_fmac_f32_e32 v4, v83, v83
	v_fmac_f32_e32 v4, v84, v84
	v_fmac_f32_e32 v4, v85, v85
	v_fmac_f32_e32 v4, v86, v86
	v_fmac_f32_e32 v4, v87, v87
	v_mul_f32_e32 v5, v88, v88
	v_fmac_f32_e32 v5, v89, v89
	v_fmac_f32_e32 v5, v90, v90
	v_fmac_f32_e32 v5, v91, v91
	v_fmac_f32_e32 v5, v92, v92
	v_fmac_f32_e32 v5, v93, v93
	v_fmac_f32_e32 v5, v94, v94
	v_fmac_f32_e32 v5, v95, v95
	v_mul_f32_e32 v6, v96, v96
	v_fmac_f32_e32 v6, v97, v97
	v_fmac_f32_e32 v6, v98, v98
	v_fmac_f32_e32 v6, v99, v99
	v_fmac_f32_e32 v6, v100, v100
	v_fmac_f32_e32 v6, v101, v101
	v_fmac_f32_e32 v6, v102, v102
	v_fmac_f32_e32 v6, v103, v103
	v_mul_f32_e32 v7, v104, v104
	v_fmac_f32_e32 v7, v105, v105
	v_fmac_f32_e32 v7, v106, v106
	v_fmac_f32_e32 v7, v107, v107
	v_fmac_f32_e32 v7, v108, v108
	v_fmac_f32_e32 v7, v109, v109
	v_fmac_f32_e32 v7, v110, v110
	v_fmac_f32_e32 v7, v111, v111
	v_mul_f32_e32 v8, v112, v112
	v_fmac_f32_e32 v8, v113, v113
	v_fmac_f32_e32 v8, v114, v114
	v_fmac_f32_e32 v8, v115, v115
	v_fmac_f32_e32 v8, v116, v116
	v_fmac_f32_e32 v8, v117, v117
	v_fmac_f32_e32 v8, v118, v118
	v_fmac_f32_e32 v8, v119, v119
	v_mul_f32_e32 v9, v120, v120
	v_fmac_f32_e32 v9, v121, v121
	v_fmac_f32_e32 v9, v122, v122
	v_fmac_f32_e32 v9, v123, v123
	v_fmac_f32_e32 v9, v124, v124
	v_fmac_f32_e32 v9, v125, v125
	v_fmac_f32_e32 v9, v126, v126
	v_fmac_f32_e32 v9, v127, v127
	v_mul_f32_e32 v10, v128, v128
	v_fmac_f32_e32 v10, v129, v129
	v_fmac_f32_e32 v10, v130, v130
	v_fmac_f32_e32 v10, v131, v131
	v_fmac_f32_e32 v10, v132, v132
	v_fmac_f32_e32 v10, v133, v133
	v_fmac_f32_e32 v10, v134, v134
	v_fmac_f32_e32 v10, v135, v135
	v_mul_f32_e32 v11, v136, v136
	v_fmac_f32_e32 v11, v137, v137
	v_fmac_f32_e32 v11, v138, v138
	v_fmac_f32_e32 v11, v139, v139
	v_fmac_f32_e32 v11, v140, v140
	v_fmac_f32_e32 v11, v141, v141
	v_fmac_f32_e32 v11, v142, v142
	v_fmac_f32_e32 v11, v143, v143
	s_nop 1
	v_add_f32_dpp v4, v4, v4 quad_perm:[1,0,3,2] row_mask:0xf bank_mask:0xf bound_ctrl:1
	v_add_f32_dpp v5, v5, v5 quad_perm:[1,0,3,2] row_mask:0xf bank_mask:0xf bound_ctrl:1
	v_add_f32_dpp v6, v6, v6 quad_perm:[1,0,3,2] row_mask:0xf bank_mask:0xf bound_ctrl:1
	v_add_f32_dpp v7, v7, v7 quad_perm:[1,0,3,2] row_mask:0xf bank_mask:0xf bound_ctrl:1
	v_add_f32_dpp v8, v8, v8 quad_perm:[1,0,3,2] row_mask:0xf bank_mask:0xf bound_ctrl:1
	v_add_f32_dpp v9, v9, v9 quad_perm:[1,0,3,2] row_mask:0xf bank_mask:0xf bound_ctrl:1
	v_add_f32_dpp v10, v10, v10 quad_perm:[1,0,3,2] row_mask:0xf bank_mask:0xf bound_ctrl:1
	v_add_f32_dpp v11, v11, v11 quad_perm:[1,0,3,2] row_mask:0xf bank_mask:0xf bound_ctrl:1
	s_nop 1
	v_add_f32_dpp v4, v4, v4 quad_perm:[2,3,0,1] row_mask:0xf bank_mask:0xf bound_ctrl:1
	v_add_f32_dpp v5, v5, v5 quad_perm:[2,3,0,1] row_mask:0xf bank_mask:0xf bound_ctrl:1
	v_add_f32_dpp v6, v6, v6 quad_perm:[2,3,0,1] row_mask:0xf bank_mask:0xf bound_ctrl:1
	v_add_f32_dpp v7, v7, v7 quad_perm:[2,3,0,1] row_mask:0xf bank_mask:0xf bound_ctrl:1
	v_add_f32_dpp v8, v8, v8 quad_perm:[2,3,0,1] row_mask:0xf bank_mask:0xf bound_ctrl:1
	v_add_f32_dpp v9, v9, v9 quad_perm:[2,3,0,1] row_mask:0xf bank_mask:0xf bound_ctrl:1
	v_add_f32_dpp v10, v10, v10 quad_perm:[2,3,0,1] row_mask:0xf bank_mask:0xf bound_ctrl:1
	v_add_f32_dpp v11, v11, v11 quad_perm:[2,3,0,1] row_mask:0xf bank_mask:0xf bound_ctrl:1
	s_nop 1
	v_add_f32_dpp v4, v4, v4 row_half_mirror row_mask:0xf bank_mask:0xf bound_ctrl:1
	v_add_f32_dpp v5, v5, v5 row_half_mirror row_mask:0xf bank_mask:0xf bound_ctrl:1
	v_add_f32_dpp v6, v6, v6 row_half_mirror row_mask:0xf bank_mask:0xf bound_ctrl:1
	v_add_f32_dpp v7, v7, v7 row_half_mirror row_mask:0xf bank_mask:0xf bound_ctrl:1
	v_add_f32_dpp v8, v8, v8 row_half_mirror row_mask:0xf bank_mask:0xf bound_ctrl:1
	v_add_f32_dpp v9, v9, v9 row_half_mirror row_mask:0xf bank_mask:0xf bound_ctrl:1
	v_add_f32_dpp v10, v10, v10 row_half_mirror row_mask:0xf bank_mask:0xf bound_ctrl:1
	v_add_f32_dpp v11, v11, v11 row_half_mirror row_mask:0xf bank_mask:0xf bound_ctrl:1
	s_nop 1
	v_add_f32_dpp v4, v4, v4 row_mirror row_mask:0xf bank_mask:0xf bound_ctrl:1
	v_add_f32_dpp v5, v5, v5 row_mirror row_mask:0xf bank_mask:0xf bound_ctrl:1
	v_add_f32_dpp v6, v6, v6 row_mirror row_mask:0xf bank_mask:0xf bound_ctrl:1
	v_add_f32_dpp v7, v7, v7 row_mirror row_mask:0xf bank_mask:0xf bound_ctrl:1
	v_add_f32_dpp v8, v8, v8 row_mirror row_mask:0xf bank_mask:0xf bound_ctrl:1
	v_add_f32_dpp v9, v9, v9 row_mirror row_mask:0xf bank_mask:0xf bound_ctrl:1
	v_add_f32_dpp v10, v10, v10 row_mirror row_mask:0xf bank_mask:0xf bound_ctrl:1
	v_add_f32_dpp v11, v11, v11 row_mirror row_mask:0xf bank_mask:0xf bound_ctrl:1
	v_lshrrev_b32_e32 v217, 6, v1
	v_and_b32_e32 v217, 12, v217
	s_lshl_b32 s52, s9, 4
	s_add_i32 s52, s52, 1024
	v_add_u32_e32 v217, s52, v217
	s_mov_b32 exec_lo, 0x10001
	s_mov_b32 exec_hi, 0x10001
	ds_write_b32 v217, v4
	ds_write_b32 v217, v5 offset:128
	ds_write_b32 v217, v6 offset:256
	ds_write_b32 v217, v7 offset:384
	ds_write_b32 v217, v8 offset:512
	ds_write_b32 v217, v9 offset:640
	ds_write_b32 v217, v10 offset:768
	ds_write_b32 v217, v11 offset:896
	s_mov_b64 exec, -1
	s_waitcnt lgkmcnt(0)
	s_barrier
	v_lshrrev_b32_e32 v218, 4, v1
	v_and_b32_e32 v218, 7, v218
	v_lshlrev_b32_e32 v217, 7, v218
	v_add_u32_e32 v217, 0x400, v217
	ds_read_b128 v[12:15], v217
	ds_read_b128 v[220:223], v217 offset:16
	s_waitcnt lgkmcnt(0)
	v_add_f32_e32 v216, v12, v13
	v_add_f32_e32 v216, v216, v14
	v_add_f32_e32 v216, v216, v15
	v_add_f32_e32 v216, v216, v220
	v_add_f32_e32 v216, v216, v221
	v_add_f32_e32 v216, v216, v222
	v_add_f32_e32 v216, v216, v223
	ds_read_b128 v[12:15], v217 offset:32
	ds_read_b128 v[220:223], v217 offset:48
	s_waitcnt lgkmcnt(0)
	v_add_f32_e32 v216, v216, v12
	v_add_f32_e32 v216, v216, v13
	v_add_f32_e32 v216, v216, v14
	v_add_f32_e32 v216, v216, v15
	v_add_f32_e32 v216, v216, v220
	v_add_f32_e32 v216, v216, v221
	v_add_f32_e32 v216, v216, v222
	v_add_f32_e32 v216, v216, v223
	ds_read_b128 v[12:15], v217 offset:64
	ds_read_b128 v[220:223], v217 offset:80
	s_waitcnt lgkmcnt(0)
	v_add_f32_e32 v216, v216, v12
	v_add_f32_e32 v216, v216, v13
	v_add_f32_e32 v216, v216, v14
	v_add_f32_e32 v216, v216, v15
	v_add_f32_e32 v216, v216, v220
	v_add_f32_e32 v216, v216, v221
	v_add_f32_e32 v216, v216, v222
	v_add_f32_e32 v216, v216, v223
	ds_read_b128 v[12:15], v217 offset:96
	ds_read_b128 v[220:223], v217 offset:112
	s_waitcnt lgkmcnt(0)
	v_add_f32_e32 v216, v216, v12
	v_add_f32_e32 v216, v216, v13
	v_add_f32_e32 v216, v216, v14
	v_add_f32_e32 v216, v216, v15
	v_add_f32_e32 v216, v216, v220
	v_add_f32_e32 v216, v216, v221
	v_add_f32_e32 v216, v216, v222
	v_add_f32_e32 v216, v216, v223
	v_mov_b32_e32 v221, 0x358637bd
	v_mov_b32_e32 v222, 0x260
	s_mov_b32 s54, 0xf800000
	v_fmamk_f32 v216, v216, 0x39800000, v221
	v_mul_f32_e32 v12, 0x4f800000, v216
	v_cmp_gt_f32_e32 vcc, s54, v216
	s_nop 1
	v_cndmask_b32_e32 v216, v216, v12, vcc
	v_sqrt_f32_e32 v12, v216
	s_nop 0
	v_add_u32_e32 v13, -1, v12
	v_add_u32_e32 v14, 1, v12
	v_fma_f32 v15, -v13, v12, v216
	v_fma_f32 v220, -v14, v12, v216
	v_cmp_ge_f32_e64 s[30:31], 0, v15
	s_nop 1
	v_cndmask_b32_e64 v12, v12, v13, s[30:31]
	v_cmp_lt_f32_e64 s[30:31], 0, v220
	s_nop 1
	v_cndmask_b32_e64 v12, v12, v14, s[30:31]
	v_mul_f32_e32 v13, 0x37800000, v12
	v_cndmask_b32_e32 v12, v12, v13, vcc
	v_cmp_class_f32_e32 vcc, v216, v222
	s_nop 1
	v_cndmask_b32_e32 v216, v12, v216, vcc
	v_div_scale_f32 v12, s[30:31], v216, v216, 1.0
	v_rcp_f32_e32 v13, v12
	v_div_scale_f32 v14, vcc, 1.0, v216, 1.0
	v_fma_f32 v15, -v12, v13, 1.0
	v_fmac_f32_e32 v13, v15, v13
	v_mul_f32_e32 v15, v14, v13
	v_fma_f32 v220, -v12, v15, v14
	v_fmac_f32_e32 v15, v220, v13
	v_fma_f32 v12, -v12, v15, v14
	v_div_fmas_f32 v12, v12, v13, v15
	v_div_fixup_f32 v216, v12, v216, 1.0
	s_mul_i32 s52, s9, 320
	s_lshl_b32 s53, s13, 5
	s_add_i32 s52, s52, s53
	s_add_i32 s52, s52, 0x800
	v_lshl_add_u32 v217, v218, 2, s52
	ds_write_b32 v217, v216
	s_nop 1
	v_readlane_b32 s20, v216, 0
	v_readlane_b32 s21, v216, 1
	v_readlane_b32 s22, v216, 2
	v_readlane_b32 s23, v216, 3
	v_readlane_b32 s24, v216, 4
	v_readlane_b32 s25, v216, 5
	v_readlane_b32 s26, v216, 6
	v_readlane_b32 s27, v216, 7
	s_lshl_b32 s53, s12, 2
	v_subrev_u32_e32 v13, s53, v217
	ds_read_b32 v14, v13
	v_add_u32_e32 v15, s15, v218
	v_cmp_le_u32_e32 vcc, s12, v15
	v_add_u32_e32 v15, 1, v15
	v_min_u32_e32 v15, s12, v15
	v_cvt_f32_u32_e32 v220, v15
	s_waitcnt lgkmcnt(0)
	v_cndmask_b32_e32 v14, 0, v14, vcc
	s_nop 1
	v_readlane_b32 s36, v14, 0
	v_readlane_b32 s37, v14, 1
	v_readlane_b32 s38, v14, 2
	v_readlane_b32 s39, v14, 3
	v_readlane_b32 s40, v14, 4
	v_readlane_b32 s41, v14, 5
	v_readlane_b32 s42, v14, 6
	v_readlane_b32 s43, v14, 7
	v_div_scale_f32 v12, s[30:31], v220, v220, 1.0
	v_rcp_f32_e32 v13, v12
	v_div_scale_f32 v14, vcc, 1.0, v220, 1.0
	v_fma_f32 v15, -v12, v13, 1.0
	v_fmac_f32_e32 v13, v15, v13
	v_mul_f32_e32 v15, v14, v13
	v_fma_f32 v221, -v12, v15, v14
	v_fmac_f32_e32 v15, v221, v13
	v_fma_f32 v12, -v12, v15, v14
	v_div_fmas_f32 v12, v12, v13, v15
	v_div_fixup_f32 v216, v12, v220, 1.0
	s_nop 1
	v_readlane_b32 s44, v216, 0
	v_readlane_b32 s45, v216, 1
	v_readlane_b32 s46, v216, 2
	v_readlane_b32 s47, v216, 3
	v_readlane_b32 s48, v216, 4
	v_readlane_b32 s49, v216, 5
	v_readlane_b32 s50, v216, 6
	v_readlane_b32 s51, v216, 7
	s_nop 1
	v_lshlrev_b32_e32 v217, 1, v1
	v_add_u32_e32 v217, s28, v217
	ds_read_b128 v[4:7], v217
	ds_read_b128 v[8:11], v217 offset:16
	s_waitcnt lgkmcnt(0)
	v_mul_f32_e32 v80, s20, v80
	v_mul_f32_e32 v81, s20, v81
	v_mul_f32_e32 v82, s20, v82
	v_mul_f32_e32 v83, s20, v83
	v_mul_f32_e32 v84, s20, v84
	v_mul_f32_e32 v85, s20, v85
	v_mul_f32_e32 v86, s20, v86
	v_mul_f32_e32 v87, s20, v87
	v_pk_mul_f32 v[80:81], v[80:81], v[4:5]
	v_pk_mul_f32 v[82:83], v[82:83], v[6:7]
	v_pk_mul_f32 v[84:85], v[84:85], v[8:9]
	v_pk_mul_f32 v[86:87], v[86:87], v[10:11]
	v_mul_f32_e32 v88, s21, v88
	v_mul_f32_e32 v89, s21, v89
	v_mul_f32_e32 v90, s21, v90
	v_mul_f32_e32 v91, s21, v91
	v_mul_f32_e32 v92, s21, v92
	v_mul_f32_e32 v93, s21, v93
	v_mul_f32_e32 v94, s21, v94
	v_mul_f32_e32 v95, s21, v95
	v_pk_mul_f32 v[88:89], v[88:89], v[4:5]
	v_pk_mul_f32 v[90:91], v[90:91], v[6:7]
	v_pk_mul_f32 v[92:93], v[92:93], v[8:9]
	v_pk_mul_f32 v[94:95], v[94:95], v[10:11]
	v_mul_f32_e32 v96, s22, v96
	v_mul_f32_e32 v97, s22, v97
	v_mul_f32_e32 v98, s22, v98
	v_mul_f32_e32 v99, s22, v99
	v_mul_f32_e32 v100, s22, v100
	v_mul_f32_e32 v101, s22, v101
	v_mul_f32_e32 v102, s22, v102
	v_mul_f32_e32 v103, s22, v103
	v_pk_mul_f32 v[96:97], v[96:97], v[4:5]
	v_pk_mul_f32 v[98:99], v[98:99], v[6:7]
	v_pk_mul_f32 v[100:101], v[100:101], v[8:9]
	v_pk_mul_f32 v[102:103], v[102:103], v[10:11]
	v_mul_f32_e32 v104, s23, v104
	v_mul_f32_e32 v105, s23, v105
	v_mul_f32_e32 v106, s23, v106
	v_mul_f32_e32 v107, s23, v107
	v_mul_f32_e32 v108, s23, v108
	v_mul_f32_e32 v109, s23, v109
	v_mul_f32_e32 v110, s23, v110
	v_mul_f32_e32 v111, s23, v111
	v_pk_mul_f32 v[104:105], v[104:105], v[4:5]
	v_pk_mul_f32 v[106:107], v[106:107], v[6:7]
	v_pk_mul_f32 v[108:109], v[108:109], v[8:9]
	v_pk_mul_f32 v[110:111], v[110:111], v[10:11]
	v_mul_f32_e32 v112, s24, v112
	v_mul_f32_e32 v113, s24, v113
	v_mul_f32_e32 v114, s24, v114
	v_mul_f32_e32 v115, s24, v115
	v_mul_f32_e32 v116, s24, v116
	v_mul_f32_e32 v117, s24, v117
	v_mul_f32_e32 v118, s24, v118
	v_mul_f32_e32 v119, s24, v119
	v_pk_mul_f32 v[112:113], v[112:113], v[4:5]
	v_pk_mul_f32 v[114:115], v[114:115], v[6:7]
	v_pk_mul_f32 v[116:117], v[116:117], v[8:9]
	v_pk_mul_f32 v[118:119], v[118:119], v[10:11]
	v_mul_f32_e32 v120, s25, v120
	v_mul_f32_e32 v121, s25, v121
	v_mul_f32_e32 v122, s25, v122
	v_mul_f32_e32 v123, s25, v123
	v_mul_f32_e32 v124, s25, v124
	v_mul_f32_e32 v125, s25, v125
	v_mul_f32_e32 v126, s25, v126
	v_mul_f32_e32 v127, s25, v127
	v_pk_mul_f32 v[120:121], v[120:121], v[4:5]
	v_pk_mul_f32 v[122:123], v[122:123], v[6:7]
	v_pk_mul_f32 v[124:125], v[124:125], v[8:9]
	v_pk_mul_f32 v[126:127], v[126:127], v[10:11]
	v_mul_f32_e32 v128, s26, v128
	v_mul_f32_e32 v129, s26, v129
	v_mul_f32_e32 v130, s26, v130
	v_mul_f32_e32 v131, s26, v131
	v_mul_f32_e32 v132, s26, v132
	v_mul_f32_e32 v133, s26, v133
	v_mul_f32_e32 v134, s26, v134
	v_mul_f32_e32 v135, s26, v135
	v_pk_mul_f32 v[128:129], v[128:129], v[4:5]
	v_pk_mul_f32 v[130:131], v[130:131], v[6:7]
	v_pk_mul_f32 v[132:133], v[132:133], v[8:9]
	v_pk_mul_f32 v[134:135], v[134:135], v[10:11]
	v_mul_f32_e32 v136, s27, v136
	v_mul_f32_e32 v137, s27, v137
	v_mul_f32_e32 v138, s27, v138
	v_mul_f32_e32 v139, s27, v139
	v_mul_f32_e32 v140, s27, v140
	v_mul_f32_e32 v141, s27, v141
	v_mul_f32_e32 v142, s27, v142
	v_mul_f32_e32 v143, s27, v143
	v_pk_mul_f32 v[136:137], v[136:137], v[4:5]
	v_pk_mul_f32 v[138:139], v[138:139], v[6:7]
	v_pk_mul_f32 v[140:141], v[140:141], v[8:9]
	v_pk_mul_f32 v[142:143], v[142:143], v[10:11]
	s_cmp_ge_u32 s13, 9
	s_cbranch_scc1 .Lp1f_w0_m1
	s_waitcnt vmcnt(16)
	s_branch .Lp1f_w1_m1

.Lp1f_w1_m1:
	v_mul_f32_e32 v144, s36, v144
	v_mul_f32_e32 v145, s36, v145
	v_mul_f32_e32 v146, s36, v146
	v_mul_f32_e32 v147, s36, v147
	v_mul_f32_e32 v148, s36, v148
	v_mul_f32_e32 v149, s36, v149
	v_mul_f32_e32 v150, s36, v150
	v_mul_f32_e32 v151, s36, v151
	v_pk_mul_f32 v[144:145], v[144:145], v[4:5]
	v_pk_mul_f32 v[146:147], v[146:147], v[6:7]
	v_pk_mul_f32 v[148:149], v[148:149], v[8:9]
	v_pk_mul_f32 v[150:151], v[150:151], v[10:11]
	v_mul_f32_e32 v152, s37, v152
	v_mul_f32_e32 v153, s37, v153
	v_mul_f32_e32 v154, s37, v154
	v_mul_f32_e32 v155, s37, v155
	v_mul_f32_e32 v156, s37, v156
	v_mul_f32_e32 v157, s37, v157
	v_mul_f32_e32 v158, s37, v158
	v_mul_f32_e32 v159, s37, v159
	v_pk_mul_f32 v[152:153], v[152:153], v[4:5]
	v_pk_mul_f32 v[154:155], v[154:155], v[6:7]
	v_pk_mul_f32 v[156:157], v[156:157], v[8:9]
	v_pk_mul_f32 v[158:159], v[158:159], v[10:11]
	v_mul_f32_e32 v160, s38, v160
	v_mul_f32_e32 v161, s38, v161
	v_mul_f32_e32 v162, s38, v162
	v_mul_f32_e32 v163, s38, v163
	v_mul_f32_e32 v164, s38, v164
	v_mul_f32_e32 v165, s38, v165
	v_mul_f32_e32 v166, s38, v166
	v_mul_f32_e32 v167, s38, v167
	v_pk_mul_f32 v[160:161], v[160:161], v[4:5]
	v_pk_mul_f32 v[162:163], v[162:163], v[6:7]
	v_pk_mul_f32 v[164:165], v[164:165], v[8:9]
	v_pk_mul_f32 v[166:167], v[166:167], v[10:11]
	v_mul_f32_e32 v168, s39, v168
	v_mul_f32_e32 v169, s39, v169
	v_mul_f32_e32 v170, s39, v170
	v_mul_f32_e32 v171, s39, v171
	v_mul_f32_e32 v172, s39, v172
	v_mul_f32_e32 v173, s39, v173
	v_mul_f32_e32 v174, s39, v174
	v_mul_f32_e32 v175, s39, v175
	v_pk_mul_f32 v[168:169], v[168:169], v[4:5]
	v_pk_mul_f32 v[170:171], v[170:171], v[6:7]
	v_pk_mul_f32 v[172:173], v[172:173], v[8:9]
	v_pk_mul_f32 v[174:175], v[174:175], v[10:11]
	v_mul_f32_e32 v176, s40, v176
	v_mul_f32_e32 v177, s40, v177
	v_mul_f32_e32 v178, s40, v178
	v_mul_f32_e32 v179, s40, v179
	v_mul_f32_e32 v180, s40, v180
	v_mul_f32_e32 v181, s40, v181
	v_mul_f32_e32 v182, s40, v182
	v_mul_f32_e32 v183, s40, v183
	v_pk_mul_f32 v[176:177], v[176:177], v[4:5]
	v_pk_mul_f32 v[178:179], v[178:179], v[6:7]
	v_pk_mul_f32 v[180:181], v[180:181], v[8:9]
	v_pk_mul_f32 v[182:183], v[182:183], v[10:11]
	v_mul_f32_e32 v184, s41, v184
	v_mul_f32_e32 v185, s41, v185
	v_mul_f32_e32 v186, s41, v186
	v_mul_f32_e32 v187, s41, v187
	v_mul_f32_e32 v188, s41, v188
	v_mul_f32_e32 v189, s41, v189
	v_mul_f32_e32 v190, s41, v190
	v_mul_f32_e32 v191, s41, v191
	v_pk_mul_f32 v[184:185], v[184:185], v[4:5]
	v_pk_mul_f32 v[186:187], v[186:187], v[6:7]
	v_pk_mul_f32 v[188:189], v[188:189], v[8:9]
	v_pk_mul_f32 v[190:191], v[190:191], v[10:11]
	v_mul_f32_e32 v192, s42, v192
	v_mul_f32_e32 v193, s42, v193
	v_mul_f32_e32 v194, s42, v194
	v_mul_f32_e32 v195, s42, v195
	v_mul_f32_e32 v196, s42, v196
	v_mul_f32_e32 v197, s42, v197
	v_mul_f32_e32 v198, s42, v198
	v_mul_f32_e32 v199, s42, v199
	v_pk_mul_f32 v[192:193], v[192:193], v[4:5]
	v_pk_mul_f32 v[194:195], v[194:195], v[6:7]
	v_pk_mul_f32 v[196:197], v[196:197], v[8:9]
	v_pk_mul_f32 v[198:199], v[198:199], v[10:11]
	v_mul_f32_e32 v200, s43, v200
	v_mul_f32_e32 v201, s43, v201
	v_mul_f32_e32 v202, s43, v202
	v_mul_f32_e32 v203, s43, v203
	v_mul_f32_e32 v204, s43, v204
	v_mul_f32_e32 v205, s43, v205
	v_mul_f32_e32 v206, s43, v206
	v_mul_f32_e32 v207, s43, v207
	v_pk_mul_f32 v[200:201], v[200:201], v[4:5]
	v_pk_mul_f32 v[202:203], v[202:203], v[6:7]
	v_pk_mul_f32 v[204:205], v[204:205], v[8:9]
	v_pk_mul_f32 v[206:207], v[206:207], v[10:11]
	v_pk_add_f32 v[208:209], v[208:209], v[80:81]
	v_pk_add_f32 v[210:211], v[210:211], v[82:83]
	v_pk_add_f32 v[212:213], v[212:213], v[84:85]
	v_pk_add_f32 v[214:215], v[214:215], v[86:87]
	v_pk_add_f32 v[208:209], v[208:209], v[144:145] neg_lo:[0,1] neg_hi:[0,1]
	v_pk_add_f32 v[210:211], v[210:211], v[146:147] neg_lo:[0,1] neg_hi:[0,1]
	v_pk_add_f32 v[212:213], v[212:213], v[148:149] neg_lo:[0,1] neg_hi:[0,1]
	v_pk_add_f32 v[214:215], v[214:215], v[150:151] neg_lo:[0,1] neg_hi:[0,1]
	v_fma_f32 v217, v208, s44, -v80
	v_fma_f32 v218, v209, s44, -v81
	v_fma_f32 v216, v210, s44, -v82
	v_fma_f32 v12, v211, s44, -v83
	v_fma_f32 v13, v212, s44, -v84
	v_fma_f32 v14, v213, s44, -v85
	v_fma_f32 v15, v214, s44, -v86
	v_fma_f32 v220, v215, s44, -v87
	v_cvt_pk_bf16_f32 v144, v217, v218
	v_cvt_pk_bf16_f32 v145, v216, v12
	v_cvt_pk_bf16_f32 v146, v13, v14
	v_cvt_pk_bf16_f32 v147, v15, v220
	s_add_i32 s52, s14, 0
	s_mov_b32 s53, 0
	s_lshl_b64 s[52:53], s[52:53], 13
	s_add_u32 s52, s52, s4
	s_addc_u32 s53, s53, s5
	global_store_dwordx2 v3, v[144:145], s[52:53]
	global_store_dwordx2 v3, v[146:147], s[52:53] offset:512
	v_pk_add_f32 v[208:209], v[208:209], v[88:89]
	v_pk_add_f32 v[210:211], v[210:211], v[90:91]
	v_pk_add_f32 v[212:213], v[212:213], v[92:93]
	v_pk_add_f32 v[214:215], v[214:215], v[94:95]
	v_pk_add_f32 v[208:209], v[208:209], v[152:153] neg_lo:[0,1] neg_hi:[0,1]
	v_pk_add_f32 v[210:211], v[210:211], v[154:155] neg_lo:[0,1] neg_hi:[0,1]
	v_pk_add_f32 v[212:213], v[212:213], v[156:157] neg_lo:[0,1] neg_hi:[0,1]
	v_pk_add_f32 v[214:215], v[214:215], v[158:159] neg_lo:[0,1] neg_hi:[0,1]
	v_fma_f32 v217, v208, s45, -v88
	v_fma_f32 v218, v209, s45, -v89
	v_fma_f32 v216, v210, s45, -v90
	v_fma_f32 v12, v211, s45, -v91
	v_fma_f32 v13, v212, s45, -v92
	v_fma_f32 v14, v213, s45, -v93
	v_fma_f32 v15, v214, s45, -v94
	v_fma_f32 v220, v215, s45, -v95
	v_cvt_pk_bf16_f32 v152, v217, v218
	v_cvt_pk_bf16_f32 v153, v216, v12
	v_cvt_pk_bf16_f32 v154, v13, v14
	v_cvt_pk_bf16_f32 v155, v15, v220
	s_add_i32 s52, s14, 1
	s_mov_b32 s53, 0
	s_lshl_b64 s[52:53], s[52:53], 13
	s_add_u32 s52, s52, s4
	s_addc_u32 s53, s53, s5
	global_store_dwordx2 v3, v[152:153], s[52:53]
	global_store_dwordx2 v3, v[154:155], s[52:53] offset:512
	v_pk_add_f32 v[208:209], v[208:209], v[96:97]
	v_pk_add_f32 v[210:211], v[210:211], v[98:99]
	v_pk_add_f32 v[212:213], v[212:213], v[100:101]
	v_pk_add_f32 v[214:215], v[214:215], v[102:103]
	v_pk_add_f32 v[208:209], v[208:209], v[160:161] neg_lo:[0,1] neg_hi:[0,1]
	v_pk_add_f32 v[210:211], v[210:211], v[162:163] neg_lo:[0,1] neg_hi:[0,1]
	v_pk_add_f32 v[212:213], v[212:213], v[164:165] neg_lo:[0,1] neg_hi:[0,1]
	v_pk_add_f32 v[214:215], v[214:215], v[166:167] neg_lo:[0,1] neg_hi:[0,1]
	v_fma_f32 v217, v208, s46, -v96
	v_fma_f32 v218, v209, s46, -v97
	v_fma_f32 v216, v210, s46, -v98
	v_fma_f32 v12, v211, s46, -v99
	v_fma_f32 v13, v212, s46, -v100
	v_fma_f32 v14, v213, s46, -v101
	v_fma_f32 v15, v214, s46, -v102
	v_fma_f32 v220, v215, s46, -v103
	v_cvt_pk_bf16_f32 v160, v217, v218
	v_cvt_pk_bf16_f32 v161, v216, v12
	v_cvt_pk_bf16_f32 v162, v13, v14
	v_cvt_pk_bf16_f32 v163, v15, v220
	s_add_i32 s52, s14, 2
	s_mov_b32 s53, 0
	s_lshl_b64 s[52:53], s[52:53], 13
	s_add_u32 s52, s52, s4
	s_addc_u32 s53, s53, s5
	global_store_dwordx2 v3, v[160:161], s[52:53]
	global_store_dwordx2 v3, v[162:163], s[52:53] offset:512
	v_pk_add_f32 v[208:209], v[208:209], v[104:105]
	v_pk_add_f32 v[210:211], v[210:211], v[106:107]
	v_pk_add_f32 v[212:213], v[212:213], v[108:109]
	v_pk_add_f32 v[214:215], v[214:215], v[110:111]
	v_pk_add_f32 v[208:209], v[208:209], v[168:169] neg_lo:[0,1] neg_hi:[0,1]
	v_pk_add_f32 v[210:211], v[210:211], v[170:171] neg_lo:[0,1] neg_hi:[0,1]
	v_pk_add_f32 v[212:213], v[212:213], v[172:173] neg_lo:[0,1] neg_hi:[0,1]
	v_pk_add_f32 v[214:215], v[214:215], v[174:175] neg_lo:[0,1] neg_hi:[0,1]
	v_fma_f32 v217, v208, s47, -v104
	v_fma_f32 v218, v209, s47, -v105
	v_fma_f32 v216, v210, s47, -v106
	v_fma_f32 v12, v211, s47, -v107
	v_fma_f32 v13, v212, s47, -v108
	v_fma_f32 v14, v213, s47, -v109
	v_fma_f32 v15, v214, s47, -v110
	v_fma_f32 v220, v215, s47, -v111
	v_cvt_pk_bf16_f32 v168, v217, v218
	v_cvt_pk_bf16_f32 v169, v216, v12
	v_cvt_pk_bf16_f32 v170, v13, v14
	v_cvt_pk_bf16_f32 v171, v15, v220
	s_add_i32 s52, s14, 3
	s_mov_b32 s53, 0
	s_lshl_b64 s[52:53], s[52:53], 13
	s_add_u32 s52, s52, s4
	s_addc_u32 s53, s53, s5
	global_store_dwordx2 v3, v[168:169], s[52:53]
	global_store_dwordx2 v3, v[170:171], s[52:53] offset:512
	v_pk_add_f32 v[208:209], v[208:209], v[112:113]
	v_pk_add_f32 v[210:211], v[210:211], v[114:115]
	v_pk_add_f32 v[212:213], v[212:213], v[116:117]
	v_pk_add_f32 v[214:215], v[214:215], v[118:119]
	v_pk_add_f32 v[208:209], v[208:209], v[176:177] neg_lo:[0,1] neg_hi:[0,1]
	v_pk_add_f32 v[210:211], v[210:211], v[178:179] neg_lo:[0,1] neg_hi:[0,1]
	v_pk_add_f32 v[212:213], v[212:213], v[180:181] neg_lo:[0,1] neg_hi:[0,1]
	v_pk_add_f32 v[214:215], v[214:215], v[182:183] neg_lo:[0,1] neg_hi:[0,1]
	v_fma_f32 v217, v208, s48, -v112
	v_fma_f32 v218, v209, s48, -v113
	v_fma_f32 v216, v210, s48, -v114
	v_fma_f32 v12, v211, s48, -v115
	v_fma_f32 v13, v212, s48, -v116
	v_fma_f32 v14, v213, s48, -v117
	v_fma_f32 v15, v214, s48, -v118
	v_fma_f32 v220, v215, s48, -v119
	v_cvt_pk_bf16_f32 v176, v217, v218
	v_cvt_pk_bf16_f32 v177, v216, v12
	v_cvt_pk_bf16_f32 v178, v13, v14
	v_cvt_pk_bf16_f32 v179, v15, v220
	s_add_i32 s52, s14, 4
	s_mov_b32 s53, 0
	s_lshl_b64 s[52:53], s[52:53], 13
	s_add_u32 s52, s52, s4
	s_addc_u32 s53, s53, s5
	global_store_dwordx2 v3, v[176:177], s[52:53]
	global_store_dwordx2 v3, v[178:179], s[52:53] offset:512
	v_pk_add_f32 v[208:209], v[208:209], v[120:121]
	v_pk_add_f32 v[210:211], v[210:211], v[122:123]
	v_pk_add_f32 v[212:213], v[212:213], v[124:125]
	v_pk_add_f32 v[214:215], v[214:215], v[126:127]
	v_pk_add_f32 v[208:209], v[208:209], v[184:185] neg_lo:[0,1] neg_hi:[0,1]
	v_pk_add_f32 v[210:211], v[210:211], v[186:187] neg_lo:[0,1] neg_hi:[0,1]
	v_pk_add_f32 v[212:213], v[212:213], v[188:189] neg_lo:[0,1] neg_hi:[0,1]
	v_pk_add_f32 v[214:215], v[214:215], v[190:191] neg_lo:[0,1] neg_hi:[0,1]
	v_fma_f32 v217, v208, s49, -v120
	v_fma_f32 v218, v209, s49, -v121
	v_fma_f32 v216, v210, s49, -v122
	v_fma_f32 v12, v211, s49, -v123
	v_fma_f32 v13, v212, s49, -v124
	v_fma_f32 v14, v213, s49, -v125
	v_fma_f32 v15, v214, s49, -v126
	v_fma_f32 v220, v215, s49, -v127
	v_cvt_pk_bf16_f32 v184, v217, v218
	v_cvt_pk_bf16_f32 v185, v216, v12
	v_cvt_pk_bf16_f32 v186, v13, v14
	v_cvt_pk_bf16_f32 v187, v15, v220
	s_add_i32 s52, s14, 5
	s_mov_b32 s53, 0
	s_lshl_b64 s[52:53], s[52:53], 13
	s_add_u32 s52, s52, s4
	s_addc_u32 s53, s53, s5
	global_store_dwordx2 v3, v[184:185], s[52:53]
	global_store_dwordx2 v3, v[186:187], s[52:53] offset:512
	v_pk_add_f32 v[208:209], v[208:209], v[128:129]
	v_pk_add_f32 v[210:211], v[210:211], v[130:131]
	v_pk_add_f32 v[212:213], v[212:213], v[132:133]
	v_pk_add_f32 v[214:215], v[214:215], v[134:135]
	v_pk_add_f32 v[208:209], v[208:209], v[192:193] neg_lo:[0,1] neg_hi:[0,1]
	v_pk_add_f32 v[210:211], v[210:211], v[194:195] neg_lo:[0,1] neg_hi:[0,1]
	v_pk_add_f32 v[212:213], v[212:213], v[196:197] neg_lo:[0,1] neg_hi:[0,1]
	v_pk_add_f32 v[214:215], v[214:215], v[198:199] neg_lo:[0,1] neg_hi:[0,1]
	v_fma_f32 v217, v208, s50, -v128
	v_fma_f32 v218, v209, s50, -v129
	v_fma_f32 v216, v210, s50, -v130
	v_fma_f32 v12, v211, s50, -v131
	v_fma_f32 v13, v212, s50, -v132
	v_fma_f32 v14, v213, s50, -v133
	v_fma_f32 v15, v214, s50, -v134
	v_fma_f32 v220, v215, s50, -v135
	v_cvt_pk_bf16_f32 v192, v217, v218
	v_cvt_pk_bf16_f32 v193, v216, v12
	v_cvt_pk_bf16_f32 v194, v13, v14
	v_cvt_pk_bf16_f32 v195, v15, v220
	s_add_i32 s52, s14, 6
	s_mov_b32 s53, 0
	s_lshl_b64 s[52:53], s[52:53], 13
	s_add_u32 s52, s52, s4
	s_addc_u32 s53, s53, s5
	global_store_dwordx2 v3, v[192:193], s[52:53]
	global_store_dwordx2 v3, v[194:195], s[52:53] offset:512
	v_pk_add_f32 v[208:209], v[208:209], v[136:137]
	v_pk_add_f32 v[210:211], v[210:211], v[138:139]
	v_pk_add_f32 v[212:213], v[212:213], v[140:141]
	v_pk_add_f32 v[214:215], v[214:215], v[142:143]
	v_pk_add_f32 v[208:209], v[208:209], v[200:201] neg_lo:[0,1] neg_hi:[0,1]
	v_pk_add_f32 v[210:211], v[210:211], v[202:203] neg_lo:[0,1] neg_hi:[0,1]
	v_pk_add_f32 v[212:213], v[212:213], v[204:205] neg_lo:[0,1] neg_hi:[0,1]
	v_pk_add_f32 v[214:215], v[214:215], v[206:207] neg_lo:[0,1] neg_hi:[0,1]
	v_fma_f32 v217, v208, s51, -v136
	v_fma_f32 v218, v209, s51, -v137
	v_fma_f32 v216, v210, s51, -v138
	v_fma_f32 v12, v211, s51, -v139
	v_fma_f32 v13, v212, s51, -v140
	v_fma_f32 v14, v213, s51, -v141
	v_fma_f32 v15, v214, s51, -v142
	v_fma_f32 v220, v215, s51, -v143
	v_cvt_pk_bf16_f32 v200, v217, v218
	v_cvt_pk_bf16_f32 v201, v216, v12
	v_cvt_pk_bf16_f32 v202, v13, v14
	v_cvt_pk_bf16_f32 v203, v15, v220
	s_add_i32 s52, s14, 7
	s_mov_b32 s53, 0
	s_lshl_b64 s[52:53], s[52:53], 13
	s_add_u32 s52, s52, s4
	s_addc_u32 s53, s53, s5
	global_store_dwordx2 v3, v[200:201], s[52:53]
	global_store_dwordx2 v3, v[202:203], s[52:53] offset:512
	s_add_i32 s13, s13, 1
	s_add_i32 s14, s14, 8
	s_add_i32 s15, s15, 8
	s_cmp_lt_u32 s13, 10
	s_cbranch_scc1 .Lp1f_loop
